# MFMA pairs ordered so four consecutive k-pairs share the first source operand (accA), no s_setprio in K-loops
# speedup vs baseline: 1.0000x; 1.0000x over previous
.LBB0_355:
	s_add_u32 s52, s22, 0xfff80080
	s_addc_u32 s53, s23, -1
	s_add_i32 s58, 0, 0x10000
	s_cmp_eq_u32 s95, 28
	s_cselect_b32 s55, s13, s53
	s_cselect_b32 s54, s91, s52
	v_add_u32_e32 v138, s58, v141
	s_cselect_b32 s53, s11, s94
	s_cselect_b32 s52, s92, s93
	s_add_i32 s59, 0, 0x14000
	ds_read_b128 v[144:147], v138
	ds_read_b128 v[148:151], v138 offset:1024
	ds_read_b128 v[152:155], v138 offset:2048
	ds_read_b128 v[156:159], v138 offset:3072
	v_add_u32_e32 v138, s59, v141
	ds_read_b128 v[160:163], v138
	ds_read_b128 v[164:167], v138 offset:1024
	ds_read_b128 v[168:171], v138 offset:2048
	ds_read_b128 v[172:175], v138 offset:3072
	v_lshl_add_u64 v[138:139], s[22:23], 0, v[134:135]
	s_add_i32 m0, s76, 0xc000
	ds_read_b128 v[176:179], v143
	ds_read_b128 v[180:183], v143 offset:1024
	ds_read_b128 v[184:187], v143 offset:2048
	ds_read_b128 v[188:191], v143 offset:3072
	ds_read_b128 v[196:199], v143 offset:4096
	ds_read_b128 v[200:203], v143 offset:5120
	ds_read_b128 v[204:207], v143 offset:6144
	ds_read_b128 v[208:211], v143 offset:7168
	global_load_lds_dwordx4 v[138:139], off
	v_lshl_add_u64 v[138:139], s[22:23], 0, v[136:137]
	s_add_i32 m0, s76, 0xe000
	s_nop 0
	global_load_lds_dwordx4 v[138:139], off
	s_waitcnt vmcnt(8)
	s_waitcnt lgkmcnt(0)
	s_barrier
	v_mfma_f32_16x16x32_bf16 v[120:123], v[144:147], v[176:179], v[120:123]
	v_mfma_f32_16x16x32_bf16 v[120:123], v[148:151], v[180:183], v[120:123]
	v_mfma_f32_16x16x32_bf16 v[104:107], v[144:147], v[184:187], v[104:107]
	v_mfma_f32_16x16x32_bf16 v[104:107], v[148:151], v[188:191], v[104:107]
	v_mfma_f32_16x16x32_bf16 v[88:91], v[144:147], v[196:199], v[88:91]
	v_mfma_f32_16x16x32_bf16 v[88:91], v[148:151], v[200:203], v[88:91]
	v_mfma_f32_16x16x32_bf16 v[72:75], v[144:147], v[204:207], v[72:75]
	v_mfma_f32_16x16x32_bf16 v[72:75], v[148:151], v[208:211], v[72:75]
	v_mfma_f32_16x16x32_bf16 v[112:115], v[152:155], v[176:179], v[112:115]
	v_mfma_f32_16x16x32_bf16 v[112:115], v[156:159], v[180:183], v[112:115]
	v_mfma_f32_16x16x32_bf16 v[96:99], v[152:155], v[184:187], v[96:99]
	v_mfma_f32_16x16x32_bf16 v[96:99], v[156:159], v[188:191], v[96:99]
	v_mfma_f32_16x16x32_bf16 v[80:83], v[152:155], v[196:199], v[80:83]
	v_mfma_f32_16x16x32_bf16 v[80:83], v[156:159], v[200:203], v[80:83]
	v_mfma_f32_16x16x32_bf16 v[64:67], v[152:155], v[204:207], v[64:67]
	v_mfma_f32_16x16x32_bf16 v[64:67], v[156:159], v[208:211], v[64:67]
	v_mfma_f32_16x16x32_bf16 v[124:127], v[160:163], v[176:179], v[124:127]
	v_mfma_f32_16x16x32_bf16 v[124:127], v[164:167], v[180:183], v[124:127]
	v_mfma_f32_16x16x32_bf16 v[108:111], v[160:163], v[184:187], v[108:111]
	v_mfma_f32_16x16x32_bf16 v[108:111], v[164:167], v[188:191], v[108:111]
	v_mfma_f32_16x16x32_bf16 v[92:95], v[160:163], v[196:199], v[92:95]
	v_mfma_f32_16x16x32_bf16 v[92:95], v[164:167], v[200:203], v[92:95]
	v_mfma_f32_16x16x32_bf16 v[76:79], v[160:163], v[204:207], v[76:79]
	v_mfma_f32_16x16x32_bf16 v[76:79], v[164:167], v[208:211], v[76:79]
	v_mfma_f32_16x16x32_bf16 v[116:119], v[168:171], v[176:179], v[116:119]
	v_mfma_f32_16x16x32_bf16 v[116:119], v[172:175], v[180:183], v[116:119]
	v_mfma_f32_16x16x32_bf16 v[100:103], v[168:171], v[184:187], v[100:103]
	v_mfma_f32_16x16x32_bf16 v[100:103], v[172:175], v[188:191], v[100:103]
	v_mfma_f32_16x16x32_bf16 v[84:87], v[168:171], v[196:199], v[84:87]
	v_mfma_f32_16x16x32_bf16 v[84:87], v[172:175], v[200:203], v[84:87]
	v_mfma_f32_16x16x32_bf16 v[68:71], v[168:171], v[204:207], v[68:71]
	v_mfma_f32_16x16x32_bf16 v[68:71], v[172:175], v[208:211], v[68:71]
	s_barrier
	s_add_i32 s58, s58, s50
	v_lshl_add_u64 v[138:139], s[52:53], 0, v[216:217]
	s_mov_b32 m0, s58
	ds_read_b128 v[176:179], v143 offset:16384
	ds_read_b128 v[180:183], v143 offset:17408
	ds_read_b128 v[184:187], v143 offset:18432
	ds_read_b128 v[188:191], v143 offset:19456
	ds_read_b128 v[196:199], v143 offset:20480
	ds_read_b128 v[200:203], v143 offset:21504
	ds_read_b128 v[204:207], v143 offset:22528
	ds_read_b128 v[208:211], v143 offset:23552
	global_load_lds_dwordx4 v[138:139], off
	s_add_i32 m0, s58, 0x2000
	s_add_u32 s96, s52, 0x80000
	v_lshl_add_u64 v[192:193], s[52:53], 0, v[132:133]
	s_addc_u32 s97, s53, 0
	s_add_i32 s58, s59, s50
	global_load_lds_dwordx4 v[192:193], off
	v_lshl_add_u64 v[212:213], s[96:97], 0, v[216:217]
	s_mov_b32 m0, s58
	v_lshl_add_u64 v[214:215], s[54:55], 0, v[130:131]
	global_load_lds_dwordx4 v[212:213], off
	v_lshl_add_u64 v[212:213], s[96:97], 0, v[132:133]
	s_add_i32 m0, s58, 0x2000
	s_nop 0
	global_load_lds_dwordx4 v[212:213], off
	v_lshl_add_u64 v[212:213], s[54:55], 0, v[128:129]
	s_mov_b32 m0, s76
	s_nop 0
	global_load_lds_dwordx4 v[212:213], off
	s_mov_b32 m0, s74
	s_nop 0
	global_load_lds_dwordx4 v[214:215], off
	s_waitcnt vmcnt(8)
	s_waitcnt lgkmcnt(0)
	s_barrier
	v_mfma_f32_16x16x32_bf16 v[56:59], v[144:147], v[176:179], v[56:59]
	v_mfma_f32_16x16x32_bf16 v[56:59], v[148:151], v[180:183], v[56:59]
	v_mfma_f32_16x16x32_bf16 v[40:43], v[144:147], v[184:187], v[40:43]
	v_mfma_f32_16x16x32_bf16 v[40:43], v[148:151], v[188:191], v[40:43]
	v_mfma_f32_16x16x32_bf16 v[24:27], v[144:147], v[196:199], v[24:27]
	v_mfma_f32_16x16x32_bf16 v[24:27], v[148:151], v[200:203], v[24:27]
	v_mfma_f32_16x16x32_bf16 v[8:11], v[144:147], v[204:207], v[8:11]
	v_mfma_f32_16x16x32_bf16 v[8:11], v[148:151], v[208:211], v[8:11]
	v_mfma_f32_16x16x32_bf16 v[48:51], v[152:155], v[176:179], v[48:51]
	v_mfma_f32_16x16x32_bf16 v[48:51], v[156:159], v[180:183], v[48:51]
	v_mfma_f32_16x16x32_bf16 v[32:35], v[152:155], v[184:187], v[32:35]
	v_mfma_f32_16x16x32_bf16 v[32:35], v[156:159], v[188:191], v[32:35]
	v_mfma_f32_16x16x32_bf16 v[16:19], v[152:155], v[196:199], v[16:19]
	v_mfma_f32_16x16x32_bf16 v[16:19], v[156:159], v[200:203], v[16:19]
	v_mfma_f32_16x16x32_bf16 v[0:3], v[152:155], v[204:207], v[0:3]
	v_mfma_f32_16x16x32_bf16 v[0:3], v[156:159], v[208:211], v[0:3]
	v_mfma_f32_16x16x32_bf16 v[60:63], v[160:163], v[176:179], v[60:63]
	v_mfma_f32_16x16x32_bf16 v[60:63], v[164:167], v[180:183], v[60:63]
	v_mfma_f32_16x16x32_bf16 v[44:47], v[160:163], v[184:187], v[44:47]
	v_mfma_f32_16x16x32_bf16 v[44:47], v[164:167], v[188:191], v[44:47]
	v_mfma_f32_16x16x32_bf16 v[28:31], v[160:163], v[196:199], v[28:31]
	v_mfma_f32_16x16x32_bf16 v[28:31], v[164:167], v[200:203], v[28:31]
	v_mfma_f32_16x16x32_bf16 v[12:15], v[160:163], v[204:207], v[12:15]
	v_mfma_f32_16x16x32_bf16 v[12:15], v[164:167], v[208:211], v[12:15]
	v_mfma_f32_16x16x32_bf16 v[52:55], v[168:171], v[176:179], v[52:55]
	v_mfma_f32_16x16x32_bf16 v[52:55], v[172:175], v[180:183], v[52:55]
	v_mfma_f32_16x16x32_bf16 v[36:39], v[168:171], v[184:187], v[36:39]
	v_mfma_f32_16x16x32_bf16 v[36:39], v[172:175], v[188:191], v[36:39]
	v_mfma_f32_16x16x32_bf16 v[20:23], v[168:171], v[196:199], v[20:23]
	v_mfma_f32_16x16x32_bf16 v[20:23], v[172:175], v[200:203], v[20:23]
	v_mfma_f32_16x16x32_bf16 v[4:7], v[168:171], v[204:207], v[4:7]
	v_mfma_f32_16x16x32_bf16 v[4:7], v[172:175], v[208:211], v[4:7]
	s_barrier
	s_add_i32 s58, 0, 0x18000
	s_add_i32 s59, 0, 0x1c000
	v_add_u32_e32 v156, s58, v141
	v_add_u32_e32 v172, s59, v141
	ds_read_b128 v[144:147], v156
	ds_read_b128 v[148:151], v156 offset:1024
	ds_read_b128 v[152:155], v156 offset:2048
	ds_read_b128 v[156:159], v156 offset:3072
	ds_read_b128 v[160:163], v172
	ds_read_b128 v[164:167], v172 offset:1024
	ds_read_b128 v[168:171], v172 offset:2048
	ds_read_b128 v[172:175], v172 offset:3072
	s_add_u32 s54, s54, 0x80000
	s_addc_u32 s55, s55, 0
	s_mov_b32 m0, s85
	v_lshl_add_u64 v[218:219], s[54:55], 0, v[128:129]
	ds_read_b128 v[176:179], v143 offset:32768
	ds_read_b128 v[180:183], v143 offset:33792
	ds_read_b128 v[184:187], v143 offset:34816
	ds_read_b128 v[188:191], v143 offset:35840
	ds_read_b128 v[196:199], v143 offset:36864
	ds_read_b128 v[200:203], v143 offset:37888
	ds_read_b128 v[204:207], v143 offset:38912
	ds_read_b128 v[208:211], v143 offset:39936
	global_load_lds_dwordx4 v[218:219], off
	v_lshl_add_u64 v[218:219], s[54:55], 0, v[130:131]
	s_mov_b32 m0, s86
	s_nop 0
	global_load_lds_dwordx4 v[218:219], off
	s_waitcnt vmcnt(8)
	s_waitcnt lgkmcnt(0)
	s_barrier
	v_mfma_f32_16x16x32_bf16 v[120:123], v[144:147], v[176:179], v[120:123]
	v_mfma_f32_16x16x32_bf16 v[120:123], v[148:151], v[180:183], v[120:123]
	v_mfma_f32_16x16x32_bf16 v[104:107], v[144:147], v[184:187], v[104:107]
	v_mfma_f32_16x16x32_bf16 v[104:107], v[148:151], v[188:191], v[104:107]
	v_mfma_f32_16x16x32_bf16 v[88:91], v[144:147], v[196:199], v[88:91]
	v_mfma_f32_16x16x32_bf16 v[88:91], v[148:151], v[200:203], v[88:91]
	v_mfma_f32_16x16x32_bf16 v[72:75], v[144:147], v[204:207], v[72:75]
	v_mfma_f32_16x16x32_bf16 v[72:75], v[148:151], v[208:211], v[72:75]
	v_mfma_f32_16x16x32_bf16 v[112:115], v[152:155], v[176:179], v[112:115]
	v_mfma_f32_16x16x32_bf16 v[112:115], v[156:159], v[180:183], v[112:115]
	v_mfma_f32_16x16x32_bf16 v[96:99], v[152:155], v[184:187], v[96:99]
	v_mfma_f32_16x16x32_bf16 v[96:99], v[156:159], v[188:191], v[96:99]
	v_mfma_f32_16x16x32_bf16 v[80:83], v[152:155], v[196:199], v[80:83]
	v_mfma_f32_16x16x32_bf16 v[80:83], v[156:159], v[200:203], v[80:83]
	v_mfma_f32_16x16x32_bf16 v[64:67], v[152:155], v[204:207], v[64:67]
	v_mfma_f32_16x16x32_bf16 v[64:67], v[156:159], v[208:211], v[64:67]
	v_mfma_f32_16x16x32_bf16 v[124:127], v[160:163], v[176:179], v[124:127]
	v_mfma_f32_16x16x32_bf16 v[124:127], v[164:167], v[180:183], v[124:127]
	v_mfma_f32_16x16x32_bf16 v[108:111], v[160:163], v[184:187], v[108:111]
	v_mfma_f32_16x16x32_bf16 v[108:111], v[164:167], v[188:191], v[108:111]
	v_mfma_f32_16x16x32_bf16 v[92:95], v[160:163], v[196:199], v[92:95]
	v_mfma_f32_16x16x32_bf16 v[92:95], v[164:167], v[200:203], v[92:95]
	v_mfma_f32_16x16x32_bf16 v[76:79], v[160:163], v[204:207], v[76:79]
	v_mfma_f32_16x16x32_bf16 v[76:79], v[164:167], v[208:211], v[76:79]
	v_mfma_f32_16x16x32_bf16 v[116:119], v[168:171], v[176:179], v[116:119]
	v_mfma_f32_16x16x32_bf16 v[116:119], v[172:175], v[180:183], v[116:119]
	v_mfma_f32_16x16x32_bf16 v[100:103], v[168:171], v[184:187], v[100:103]
	v_mfma_f32_16x16x32_bf16 v[100:103], v[172:175], v[188:191], v[100:103]
	v_mfma_f32_16x16x32_bf16 v[84:87], v[168:171], v[196:199], v[84:87]
	v_mfma_f32_16x16x32_bf16 v[84:87], v[172:175], v[200:203], v[84:87]
	v_mfma_f32_16x16x32_bf16 v[68:71], v[168:171], v[204:207], v[68:71]
	v_mfma_f32_16x16x32_bf16 v[68:71], v[172:175], v[208:211], v[68:71]
	s_barrier
	s_add_i32 s54, s58, s50
	v_lshl_add_u64 v[138:139], v[138:139], 0, s[60:61]
	s_mov_b32 m0, s54
	ds_read_b128 v[176:179], v143 offset:49152
	ds_read_b128 v[180:183], v143 offset:50176
	ds_read_b128 v[184:187], v143 offset:51200
	ds_read_b128 v[188:191], v143 offset:52224
	ds_read_b128 v[196:199], v143 offset:53248
	ds_read_b128 v[200:203], v143 offset:54272
	ds_read_b128 v[204:207], v143 offset:55296
	ds_read_b128 v[208:211], v143 offset:56320
	global_load_lds_dwordx4 v[138:139], off
	s_add_i32 m0, s54, 0x2000
	s_add_u32 s52, s52, 0x80080
	v_lshl_add_u64 v[138:139], v[192:193], 0, s[60:61]
	s_addc_u32 s53, s53, 0
	s_add_i32 s54, s59, s50
	global_load_lds_dwordx4 v[138:139], off
	v_lshl_add_u64 v[138:139], s[52:53], 0, v[216:217]
	s_mov_b32 m0, s54
	s_nop 0
	global_load_lds_dwordx4 v[138:139], off
	v_lshl_add_u64 v[138:139], s[52:53], 0, v[132:133]
	s_add_i32 m0, s54, 0x2000
	s_nop 0
	global_load_lds_dwordx4 v[138:139], off
	v_lshl_add_u64 v[138:139], v[212:213], 0, s[60:61]
	s_mov_b32 m0, s87
	s_nop 0
	global_load_lds_dwordx4 v[138:139], off
	v_lshl_add_u64 v[138:139], v[214:215], 0, s[60:61]
	s_mov_b32 m0, s88
	s_nop 0
	global_load_lds_dwordx4 v[138:139], off
	s_waitcnt vmcnt(8)
	s_waitcnt lgkmcnt(0)
	s_barrier
	v_mfma_f32_16x16x32_bf16 v[56:59], v[144:147], v[176:179], v[56:59]
	v_mfma_f32_16x16x32_bf16 v[56:59], v[148:151], v[180:183], v[56:59]
	v_mfma_f32_16x16x32_bf16 v[40:43], v[144:147], v[184:187], v[40:43]
	v_mfma_f32_16x16x32_bf16 v[40:43], v[148:151], v[188:191], v[40:43]
	v_mfma_f32_16x16x32_bf16 v[24:27], v[144:147], v[196:199], v[24:27]
	v_mfma_f32_16x16x32_bf16 v[24:27], v[148:151], v[200:203], v[24:27]
	v_mfma_f32_16x16x32_bf16 v[8:11], v[144:147], v[204:207], v[8:11]
	v_mfma_f32_16x16x32_bf16 v[8:11], v[148:151], v[208:211], v[8:11]
	v_mfma_f32_16x16x32_bf16 v[48:51], v[152:155], v[176:179], v[48:51]
	v_mfma_f32_16x16x32_bf16 v[48:51], v[156:159], v[180:183], v[48:51]
	v_mfma_f32_16x16x32_bf16 v[32:35], v[152:155], v[184:187], v[32:35]
	v_mfma_f32_16x16x32_bf16 v[32:35], v[156:159], v[188:191], v[32:35]
	v_mfma_f32_16x16x32_bf16 v[16:19], v[152:155], v[196:199], v[16:19]
	v_mfma_f32_16x16x32_bf16 v[16:19], v[156:159], v[200:203], v[16:19]
	v_mfma_f32_16x16x32_bf16 v[0:3], v[152:155], v[204:207], v[0:3]
	v_mfma_f32_16x16x32_bf16 v[0:3], v[156:159], v[208:211], v[0:3]
	v_mfma_f32_16x16x32_bf16 v[60:63], v[160:163], v[176:179], v[60:63]
	v_mfma_f32_16x16x32_bf16 v[60:63], v[164:167], v[180:183], v[60:63]
	v_mfma_f32_16x16x32_bf16 v[44:47], v[160:163], v[184:187], v[44:47]
	v_mfma_f32_16x16x32_bf16 v[44:47], v[164:167], v[188:191], v[44:47]
	v_mfma_f32_16x16x32_bf16 v[28:31], v[160:163], v[196:199], v[28:31]
	v_mfma_f32_16x16x32_bf16 v[28:31], v[164:167], v[200:203], v[28:31]
	v_mfma_f32_16x16x32_bf16 v[12:15], v[160:163], v[204:207], v[12:15]
	v_mfma_f32_16x16x32_bf16 v[12:15], v[164:167], v[208:211], v[12:15]
	v_mfma_f32_16x16x32_bf16 v[52:55], v[168:171], v[176:179], v[52:55]
	v_mfma_f32_16x16x32_bf16 v[52:55], v[172:175], v[180:183], v[52:55]
	v_mfma_f32_16x16x32_bf16 v[36:39], v[168:171], v[184:187], v[36:39]
	v_mfma_f32_16x16x32_bf16 v[36:39], v[172:175], v[188:191], v[36:39]
	v_mfma_f32_16x16x32_bf16 v[20:23], v[168:171], v[196:199], v[20:23]
	v_mfma_f32_16x16x32_bf16 v[20:23], v[172:175], v[200:203], v[20:23]
	v_mfma_f32_16x16x32_bf16 v[4:7], v[168:171], v[204:207], v[4:7]
	v_mfma_f32_16x16x32_bf16 v[4:7], v[172:175], v[208:211], v[4:7]
	s_barrier
	s_add_i32 s95, s95, 2
	s_add_u32 s22, s22, 0x100
	s_addc_u32 s23, s23, 0
	s_add_u32 s93, s93, 0x100
	s_addc_u32 s94, s94, 0
	s_cmp_gt_u32 s95, 29
	s_cbranch_scc0 .LBB0_355
	s_and_b64 vcc, exec, s[38:39]
	s_cbranch_vccz .LBB0_358
	s_barrier

.LBB0_560:
	s_add_u32 s22, s18, 0x100
	s_addc_u32 s23, s19, 0
	s_add_i32 s58, 0, 0x10000
	s_cmpk_eq_i32 s96, 0x54
	s_cselect_b32 s55, s7, s23
	s_cselect_b32 s54, s6, s22
	s_cselect_b32 s53, s17, s95
	s_cselect_b32 s52, s16, s94
	s_add_i32 s59, 0, 0x14000
	v_add_u32_e32 v140, s58, v196
	v_add_u32_e32 v166, s59, v196
	ds_read_b128 v[128:131], v140
	ds_read_b128 v[132:135], v140 offset:1024
	ds_read_b128 v[136:139], v140 offset:2048
	ds_read_b128 v[140:143], v140 offset:3072
	ds_read_b128 v[144:147], v166
	ds_read_b128 v[148:151], v166 offset:1024
	ds_read_b128 v[152:155], v166 offset:2048
	ds_read_b128 v[166:169], v166 offset:3072
	v_lshl_add_u64 v[208:209], s[18:19], 0, v[162:163]
	s_add_i32 m0, s76, 0xc000
	ds_read_b128 v[170:173], v198
	ds_read_b128 v[174:177], v198 offset:1024
	ds_read_b128 v[178:181], v198 offset:2048
	ds_read_b128 v[182:185], v198 offset:3072
	ds_read_b128 v[186:189], v198 offset:4096
	ds_read_b128 v[190:193], v198 offset:5120
	ds_read_b128 v[200:203], v198 offset:6144
	ds_read_b128 v[204:207], v198 offset:7168
	global_load_lds_dwordx4 v[208:209], off
	v_lshl_add_u64 v[208:209], s[18:19], 0, v[164:165]
	s_add_i32 m0, s76, 0xe000
	s_nop 0
	global_load_lds_dwordx4 v[208:209], off
	s_waitcnt vmcnt(8)
	s_waitcnt lgkmcnt(0)
	s_barrier
	v_mfma_f32_16x16x32_bf16 v[124:127], v[128:131], v[170:173], v[124:127]
	v_mfma_f32_16x16x32_bf16 v[124:127], v[132:135], v[174:177], v[124:127]
	v_mfma_f32_16x16x32_bf16 v[108:111], v[128:131], v[178:181], v[108:111]
	v_mfma_f32_16x16x32_bf16 v[108:111], v[132:135], v[182:185], v[108:111]
	v_mfma_f32_16x16x32_bf16 v[92:95], v[128:131], v[186:189], v[92:95]
	v_mfma_f32_16x16x32_bf16 v[92:95], v[132:135], v[190:193], v[92:95]
	v_mfma_f32_16x16x32_bf16 v[76:79], v[128:131], v[200:203], v[76:79]
	v_mfma_f32_16x16x32_bf16 v[76:79], v[132:135], v[204:207], v[76:79]
	v_mfma_f32_16x16x32_bf16 v[120:123], v[136:139], v[170:173], v[120:123]
	v_mfma_f32_16x16x32_bf16 v[120:123], v[140:143], v[174:177], v[120:123]
	v_mfma_f32_16x16x32_bf16 v[104:107], v[136:139], v[178:181], v[104:107]
	v_mfma_f32_16x16x32_bf16 v[104:107], v[140:143], v[182:185], v[104:107]
	v_mfma_f32_16x16x32_bf16 v[88:91], v[136:139], v[186:189], v[88:91]
	v_mfma_f32_16x16x32_bf16 v[88:91], v[140:143], v[190:193], v[88:91]
	v_mfma_f32_16x16x32_bf16 v[72:75], v[136:139], v[200:203], v[72:75]
	v_mfma_f32_16x16x32_bf16 v[72:75], v[140:143], v[204:207], v[72:75]
	v_mfma_f32_16x16x32_bf16 v[116:119], v[144:147], v[170:173], v[116:119]
	v_mfma_f32_16x16x32_bf16 v[116:119], v[148:151], v[174:177], v[116:119]
	v_mfma_f32_16x16x32_bf16 v[100:103], v[144:147], v[178:181], v[100:103]
	v_mfma_f32_16x16x32_bf16 v[100:103], v[148:151], v[182:185], v[100:103]
	v_mfma_f32_16x16x32_bf16 v[84:87], v[144:147], v[186:189], v[84:87]
	v_mfma_f32_16x16x32_bf16 v[84:87], v[148:151], v[190:193], v[84:87]
	v_mfma_f32_16x16x32_bf16 v[68:71], v[144:147], v[200:203], v[68:71]
	v_mfma_f32_16x16x32_bf16 v[68:71], v[148:151], v[204:207], v[68:71]
	v_mfma_f32_16x16x32_bf16 v[112:115], v[152:155], v[170:173], v[112:115]
	v_mfma_f32_16x16x32_bf16 v[112:115], v[166:169], v[174:177], v[112:115]
	v_mfma_f32_16x16x32_bf16 v[96:99], v[152:155], v[178:181], v[96:99]
	v_mfma_f32_16x16x32_bf16 v[96:99], v[166:169], v[182:185], v[96:99]
	v_mfma_f32_16x16x32_bf16 v[80:83], v[152:155], v[186:189], v[80:83]
	v_mfma_f32_16x16x32_bf16 v[80:83], v[166:169], v[190:193], v[80:83]
	v_mfma_f32_16x16x32_bf16 v[64:67], v[152:155], v[200:203], v[64:67]
	v_mfma_f32_16x16x32_bf16 v[64:67], v[166:169], v[204:207], v[64:67]
	s_barrier
	s_add_i32 s18, s58, s50
	v_lshl_add_u64 v[208:209], s[52:53], 0, v[216:217]
	s_mov_b32 m0, s18
	ds_read_b128 v[170:173], v198 offset:16384
	ds_read_b128 v[174:177], v198 offset:17408
	ds_read_b128 v[178:181], v198 offset:18432
	ds_read_b128 v[182:185], v198 offset:19456
	ds_read_b128 v[186:189], v198 offset:20480
	ds_read_b128 v[190:193], v198 offset:21504
	ds_read_b128 v[200:203], v198 offset:22528
	ds_read_b128 v[204:207], v198 offset:23552
	global_load_lds_dwordx4 v[208:209], off
	s_add_i32 m0, s18, 0x2000
	s_add_u32 s18, s52, 0x164000
	v_lshl_add_u64 v[210:211], s[52:53], 0, v[160:161]
	s_addc_u32 s19, s53, 0
	s_add_i32 s58, s59, s50
	global_load_lds_dwordx4 v[210:211], off
	v_lshl_add_u64 v[212:213], s[18:19], 0, v[216:217]
	s_mov_b32 m0, s58
	v_lshl_add_u64 v[214:215], s[54:55], 0, v[158:159]
	global_load_lds_dwordx4 v[212:213], off
	v_lshl_add_u64 v[212:213], s[18:19], 0, v[160:161]
	s_add_i32 m0, s58, 0x2000
	s_nop 0
	global_load_lds_dwordx4 v[212:213], off
	v_lshl_add_u64 v[212:213], s[54:55], 0, v[156:157]
	s_mov_b32 m0, s76
	s_nop 0
	global_load_lds_dwordx4 v[212:213], off
	s_mov_b32 m0, s45
	s_nop 0
	global_load_lds_dwordx4 v[214:215], off
	s_waitcnt vmcnt(8)
	s_waitcnt lgkmcnt(0)
	s_barrier
	v_mfma_f32_16x16x32_bf16 v[60:63], v[128:131], v[170:173], v[60:63]
	v_mfma_f32_16x16x32_bf16 v[60:63], v[132:135], v[174:177], v[60:63]
	v_mfma_f32_16x16x32_bf16 v[44:47], v[128:131], v[178:181], v[44:47]
	v_mfma_f32_16x16x32_bf16 v[44:47], v[132:135], v[182:185], v[44:47]
	v_mfma_f32_16x16x32_bf16 v[28:31], v[128:131], v[186:189], v[28:31]
	v_mfma_f32_16x16x32_bf16 v[28:31], v[132:135], v[190:193], v[28:31]
	v_mfma_f32_16x16x32_bf16 v[12:15], v[128:131], v[200:203], v[12:15]
	v_mfma_f32_16x16x32_bf16 v[12:15], v[132:135], v[204:207], v[12:15]
	v_mfma_f32_16x16x32_bf16 v[56:59], v[136:139], v[170:173], v[56:59]
	v_mfma_f32_16x16x32_bf16 v[56:59], v[140:143], v[174:177], v[56:59]
	v_mfma_f32_16x16x32_bf16 v[40:43], v[136:139], v[178:181], v[40:43]
	v_mfma_f32_16x16x32_bf16 v[40:43], v[140:143], v[182:185], v[40:43]
	v_mfma_f32_16x16x32_bf16 v[24:27], v[136:139], v[186:189], v[24:27]
	v_mfma_f32_16x16x32_bf16 v[24:27], v[140:143], v[190:193], v[24:27]
	v_mfma_f32_16x16x32_bf16 v[8:11], v[136:139], v[200:203], v[8:11]
	v_mfma_f32_16x16x32_bf16 v[8:11], v[140:143], v[204:207], v[8:11]
	v_mfma_f32_16x16x32_bf16 v[52:55], v[144:147], v[170:173], v[52:55]
	v_mfma_f32_16x16x32_bf16 v[52:55], v[148:151], v[174:177], v[52:55]
	v_mfma_f32_16x16x32_bf16 v[36:39], v[144:147], v[178:181], v[36:39]
	v_mfma_f32_16x16x32_bf16 v[36:39], v[148:151], v[182:185], v[36:39]
	v_mfma_f32_16x16x32_bf16 v[20:23], v[144:147], v[186:189], v[20:23]
	v_mfma_f32_16x16x32_bf16 v[20:23], v[148:151], v[190:193], v[20:23]
	v_mfma_f32_16x16x32_bf16 v[4:7], v[144:147], v[200:203], v[4:7]
	v_mfma_f32_16x16x32_bf16 v[4:7], v[148:151], v[204:207], v[4:7]
	v_mfma_f32_16x16x32_bf16 v[48:51], v[152:155], v[170:173], v[48:51]
	v_mfma_f32_16x16x32_bf16 v[48:51], v[166:169], v[174:177], v[48:51]
	v_mfma_f32_16x16x32_bf16 v[32:35], v[152:155], v[178:181], v[32:35]
	v_mfma_f32_16x16x32_bf16 v[32:35], v[166:169], v[182:185], v[32:35]
	v_mfma_f32_16x16x32_bf16 v[16:19], v[152:155], v[186:189], v[16:19]
	v_mfma_f32_16x16x32_bf16 v[16:19], v[166:169], v[190:193], v[16:19]
	v_mfma_f32_16x16x32_bf16 v[0:3], v[152:155], v[200:203], v[0:3]
	v_mfma_f32_16x16x32_bf16 v[0:3], v[166:169], v[204:207], v[0:3]
	s_barrier
	s_add_i32 s58, 0, 0x18000
	s_add_i32 s59, 0, 0x1c000
	v_add_u32_e32 v140, s58, v196
	v_add_u32_e32 v166, s59, v196
	ds_read_b128 v[128:131], v140
	ds_read_b128 v[132:135], v140 offset:1024
	ds_read_b128 v[136:139], v140 offset:2048
	ds_read_b128 v[140:143], v140 offset:3072
	ds_read_b128 v[144:147], v166
	ds_read_b128 v[148:151], v166 offset:1024
	ds_read_b128 v[152:155], v166 offset:2048
	ds_read_b128 v[166:169], v166 offset:3072
	s_add_u32 s18, s54, 0x164000
	s_addc_u32 s19, s55, 0
	s_mov_b32 m0, s65
	v_lshl_add_u64 v[218:219], s[18:19], 0, v[156:157]
	ds_read_b128 v[170:173], v198 offset:32768
	ds_read_b128 v[174:177], v198 offset:33792
	ds_read_b128 v[178:181], v198 offset:34816
	ds_read_b128 v[182:185], v198 offset:35840
	ds_read_b128 v[186:189], v198 offset:36864
	ds_read_b128 v[190:193], v198 offset:37888
	ds_read_b128 v[200:203], v198 offset:38912
	ds_read_b128 v[204:207], v198 offset:39936
	global_load_lds_dwordx4 v[218:219], off
	v_lshl_add_u64 v[218:219], s[18:19], 0, v[158:159]
	s_mov_b32 m0, s72
	s_nop 0
	global_load_lds_dwordx4 v[218:219], off
	s_waitcnt vmcnt(8)
	s_waitcnt lgkmcnt(0)
	s_barrier
	v_mfma_f32_16x16x32_bf16 v[124:127], v[128:131], v[170:173], v[124:127]
	v_mfma_f32_16x16x32_bf16 v[124:127], v[132:135], v[174:177], v[124:127]
	v_mfma_f32_16x16x32_bf16 v[108:111], v[128:131], v[178:181], v[108:111]
	v_mfma_f32_16x16x32_bf16 v[108:111], v[132:135], v[182:185], v[108:111]
	v_mfma_f32_16x16x32_bf16 v[92:95], v[128:131], v[186:189], v[92:95]
	v_mfma_f32_16x16x32_bf16 v[92:95], v[132:135], v[190:193], v[92:95]
	v_mfma_f32_16x16x32_bf16 v[76:79], v[128:131], v[200:203], v[76:79]
	v_mfma_f32_16x16x32_bf16 v[76:79], v[132:135], v[204:207], v[76:79]
	v_mfma_f32_16x16x32_bf16 v[120:123], v[136:139], v[170:173], v[120:123]
	v_mfma_f32_16x16x32_bf16 v[120:123], v[140:143], v[174:177], v[120:123]
	v_mfma_f32_16x16x32_bf16 v[104:107], v[136:139], v[178:181], v[104:107]
	v_mfma_f32_16x16x32_bf16 v[104:107], v[140:143], v[182:185], v[104:107]
	v_mfma_f32_16x16x32_bf16 v[88:91], v[136:139], v[186:189], v[88:91]
	v_mfma_f32_16x16x32_bf16 v[88:91], v[140:143], v[190:193], v[88:91]
	v_mfma_f32_16x16x32_bf16 v[72:75], v[136:139], v[200:203], v[72:75]
	v_mfma_f32_16x16x32_bf16 v[72:75], v[140:143], v[204:207], v[72:75]
	v_mfma_f32_16x16x32_bf16 v[116:119], v[144:147], v[170:173], v[116:119]
	v_mfma_f32_16x16x32_bf16 v[116:119], v[148:151], v[174:177], v[116:119]
	v_mfma_f32_16x16x32_bf16 v[100:103], v[144:147], v[178:181], v[100:103]
	v_mfma_f32_16x16x32_bf16 v[100:103], v[148:151], v[182:185], v[100:103]
	v_mfma_f32_16x16x32_bf16 v[84:87], v[144:147], v[186:189], v[84:87]
	v_mfma_f32_16x16x32_bf16 v[84:87], v[148:151], v[190:193], v[84:87]
	v_mfma_f32_16x16x32_bf16 v[68:71], v[144:147], v[200:203], v[68:71]
	v_mfma_f32_16x16x32_bf16 v[68:71], v[148:151], v[204:207], v[68:71]
	v_mfma_f32_16x16x32_bf16 v[112:115], v[152:155], v[170:173], v[112:115]
	v_mfma_f32_16x16x32_bf16 v[112:115], v[166:169], v[174:177], v[112:115]
	v_mfma_f32_16x16x32_bf16 v[96:99], v[152:155], v[178:181], v[96:99]
	v_mfma_f32_16x16x32_bf16 v[96:99], v[166:169], v[182:185], v[96:99]
	v_mfma_f32_16x16x32_bf16 v[80:83], v[152:155], v[186:189], v[80:83]
	v_mfma_f32_16x16x32_bf16 v[80:83], v[166:169], v[190:193], v[80:83]
	v_mfma_f32_16x16x32_bf16 v[64:67], v[152:155], v[200:203], v[64:67]
	v_mfma_f32_16x16x32_bf16 v[64:67], v[166:169], v[204:207], v[64:67]
	s_barrier
	s_add_i32 s18, s58, s50
	v_lshl_add_u64 v[208:209], v[208:209], 0, s[60:61]
	s_mov_b32 m0, s18
	ds_read_b128 v[170:173], v198 offset:49152
	ds_read_b128 v[174:177], v198 offset:50176
	ds_read_b128 v[178:181], v198 offset:51200
	ds_read_b128 v[182:185], v198 offset:52224
	ds_read_b128 v[186:189], v198 offset:53248
	ds_read_b128 v[190:193], v198 offset:54272
	ds_read_b128 v[200:203], v198 offset:55296
	ds_read_b128 v[204:207], v198 offset:56320
	global_load_lds_dwordx4 v[208:209], off
	s_add_i32 m0, s18, 0x2000
	s_add_u32 s18, s52, 0x164080
	v_lshl_add_u64 v[208:209], v[210:211], 0, s[60:61]
	s_addc_u32 s19, s53, 0
	s_add_i32 s52, s59, s50
	global_load_lds_dwordx4 v[208:209], off
	v_lshl_add_u64 v[208:209], s[18:19], 0, v[216:217]
	s_mov_b32 m0, s52
	s_nop 0
	global_load_lds_dwordx4 v[208:209], off
	v_lshl_add_u64 v[208:209], s[18:19], 0, v[160:161]
	s_add_i32 m0, s52, 0x2000
	s_nop 0
	global_load_lds_dwordx4 v[208:209], off
	v_lshl_add_u64 v[208:209], v[212:213], 0, s[60:61]
	s_mov_b32 m0, s86
	s_nop 0
	global_load_lds_dwordx4 v[208:209], off
	v_lshl_add_u64 v[208:209], v[214:215], 0, s[60:61]
	s_mov_b32 m0, s87
	s_nop 0
	global_load_lds_dwordx4 v[208:209], off
	s_waitcnt vmcnt(8)
	s_waitcnt lgkmcnt(0)
	s_barrier
	v_mfma_f32_16x16x32_bf16 v[60:63], v[128:131], v[170:173], v[60:63]
	v_mfma_f32_16x16x32_bf16 v[60:63], v[132:135], v[174:177], v[60:63]
	v_mfma_f32_16x16x32_bf16 v[44:47], v[128:131], v[178:181], v[44:47]
	v_mfma_f32_16x16x32_bf16 v[44:47], v[132:135], v[182:185], v[44:47]
	v_mfma_f32_16x16x32_bf16 v[28:31], v[128:131], v[186:189], v[28:31]
	v_mfma_f32_16x16x32_bf16 v[28:31], v[132:135], v[190:193], v[28:31]
	v_mfma_f32_16x16x32_bf16 v[12:15], v[128:131], v[200:203], v[12:15]
	v_mfma_f32_16x16x32_bf16 v[12:15], v[132:135], v[204:207], v[12:15]
	v_mfma_f32_16x16x32_bf16 v[56:59], v[136:139], v[170:173], v[56:59]
	v_mfma_f32_16x16x32_bf16 v[56:59], v[140:143], v[174:177], v[56:59]
	v_mfma_f32_16x16x32_bf16 v[40:43], v[136:139], v[178:181], v[40:43]
	v_mfma_f32_16x16x32_bf16 v[40:43], v[140:143], v[182:185], v[40:43]
	v_mfma_f32_16x16x32_bf16 v[24:27], v[136:139], v[186:189], v[24:27]
	v_mfma_f32_16x16x32_bf16 v[24:27], v[140:143], v[190:193], v[24:27]
	v_mfma_f32_16x16x32_bf16 v[8:11], v[136:139], v[200:203], v[8:11]
	v_mfma_f32_16x16x32_bf16 v[8:11], v[140:143], v[204:207], v[8:11]
	v_mfma_f32_16x16x32_bf16 v[52:55], v[144:147], v[170:173], v[52:55]
	v_mfma_f32_16x16x32_bf16 v[52:55], v[148:151], v[174:177], v[52:55]
	v_mfma_f32_16x16x32_bf16 v[36:39], v[144:147], v[178:181], v[36:39]
	v_mfma_f32_16x16x32_bf16 v[36:39], v[148:151], v[182:185], v[36:39]
	v_mfma_f32_16x16x32_bf16 v[20:23], v[144:147], v[186:189], v[20:23]
	v_mfma_f32_16x16x32_bf16 v[20:23], v[148:151], v[190:193], v[20:23]
	v_mfma_f32_16x16x32_bf16 v[4:7], v[144:147], v[200:203], v[4:7]
	v_mfma_f32_16x16x32_bf16 v[4:7], v[148:151], v[204:207], v[4:7]
	v_mfma_f32_16x16x32_bf16 v[48:51], v[152:155], v[170:173], v[48:51]
	v_mfma_f32_16x16x32_bf16 v[48:51], v[166:169], v[174:177], v[48:51]
	v_mfma_f32_16x16x32_bf16 v[32:35], v[152:155], v[178:181], v[32:35]
	v_mfma_f32_16x16x32_bf16 v[32:35], v[166:169], v[182:185], v[32:35]
	v_mfma_f32_16x16x32_bf16 v[16:19], v[152:155], v[186:189], v[16:19]
	v_mfma_f32_16x16x32_bf16 v[16:19], v[166:169], v[190:193], v[16:19]
	v_mfma_f32_16x16x32_bf16 v[0:3], v[152:155], v[200:203], v[0:3]
	v_mfma_f32_16x16x32_bf16 v[0:3], v[166:169], v[204:207], v[0:3]
	s_barrier
	s_add_i32 s96, s96, 2
	s_add_u32 s94, s94, 0x100
	s_addc_u32 s95, s95, 0
	s_cmpk_gt_u32 s96, 0x55
	s_mov_b64 s[18:19], s[22:23]
	s_cbranch_scc0 .LBB0_560
	s_and_b64 vcc, exec, s[38:39]
	s_cbranch_vccz .LBB0_563
	s_barrier

.LBB0_827:
	s_add_u32 s52, s88, 0xfff80080
	s_addc_u32 s53, s89, -1
	s_add_i32 s58, 0, 0x10000
	s_cmp_eq_u32 vcc_hi, 28
	s_cselect_b32 s55, s7, s53
	s_cselect_b32 s54, s17, s52
	s_cselect_b32 s53, s15, s91
	s_cselect_b32 s52, vcc_lo, s90
	s_add_i32 s81, 0, 0x14000
	v_add_u32_e32 v140, s58, v197
	v_add_u32_e32 v156, s81, v197
	ds_read_b128 v[128:131], v140
	ds_read_b128 v[132:135], v140 offset:1024
	ds_read_b128 v[136:139], v140 offset:2048
	ds_read_b128 v[140:143], v140 offset:3072
	ds_read_b128 v[144:147], v156
	ds_read_b128 v[148:151], v156 offset:1024
	ds_read_b128 v[152:155], v156 offset:2048
	ds_read_b128 v[156:159], v156 offset:3072
	v_lshl_add_u64 v[198:199], s[88:89], 0, v[192:193]
	s_add_i32 m0, s76, 0xc000
	ds_read_b128 v[160:163], v203
	ds_read_b128 v[164:167], v203 offset:1024
	ds_read_b128 v[168:171], v203 offset:2048
	ds_read_b128 v[172:175], v203 offset:3072
	ds_read_b128 v[204:207], v203 offset:4096
	ds_read_b128 v[208:211], v203 offset:5120
	ds_read_b128 v[212:215], v203 offset:6144
	ds_read_b128 v[218:221], v203 offset:7168
	global_load_lds_dwordx4 v[198:199], off
	v_lshl_add_u64 v[198:199], s[88:89], 0, v[194:195]
	s_add_i32 m0, s76, 0xe000
	s_nop 0
	global_load_lds_dwordx4 v[198:199], off
	s_waitcnt vmcnt(8)
	s_waitcnt lgkmcnt(0)
	s_barrier
	v_mfma_f32_16x16x32_bf16 v[124:127], v[128:131], v[160:163], v[124:127]
	v_mfma_f32_16x16x32_bf16 v[124:127], v[132:135], v[164:167], v[124:127]
	v_mfma_f32_16x16x32_bf16 v[108:111], v[128:131], v[168:171], v[108:111]
	v_mfma_f32_16x16x32_bf16 v[108:111], v[132:135], v[172:175], v[108:111]
	v_mfma_f32_16x16x32_bf16 v[92:95], v[128:131], v[204:207], v[92:95]
	v_mfma_f32_16x16x32_bf16 v[92:95], v[132:135], v[208:211], v[92:95]
	v_mfma_f32_16x16x32_bf16 v[76:79], v[128:131], v[212:215], v[76:79]
	v_mfma_f32_16x16x32_bf16 v[76:79], v[132:135], v[218:221], v[76:79]
	v_mfma_f32_16x16x32_bf16 v[120:123], v[136:139], v[160:163], v[120:123]
	v_mfma_f32_16x16x32_bf16 v[120:123], v[140:143], v[164:167], v[120:123]
	v_mfma_f32_16x16x32_bf16 v[104:107], v[136:139], v[168:171], v[104:107]
	v_mfma_f32_16x16x32_bf16 v[104:107], v[140:143], v[172:175], v[104:107]
	v_mfma_f32_16x16x32_bf16 v[88:91], v[136:139], v[204:207], v[88:91]
	v_mfma_f32_16x16x32_bf16 v[88:91], v[140:143], v[208:211], v[88:91]
	v_mfma_f32_16x16x32_bf16 v[72:75], v[136:139], v[212:215], v[72:75]
	v_mfma_f32_16x16x32_bf16 v[72:75], v[140:143], v[218:221], v[72:75]
	v_mfma_f32_16x16x32_bf16 v[116:119], v[144:147], v[160:163], v[116:119]
	v_mfma_f32_16x16x32_bf16 v[116:119], v[148:151], v[164:167], v[116:119]
	v_mfma_f32_16x16x32_bf16 v[100:103], v[144:147], v[168:171], v[100:103]
	v_mfma_f32_16x16x32_bf16 v[100:103], v[148:151], v[172:175], v[100:103]
	v_mfma_f32_16x16x32_bf16 v[84:87], v[144:147], v[204:207], v[84:87]
	v_mfma_f32_16x16x32_bf16 v[84:87], v[148:151], v[208:211], v[84:87]
	v_mfma_f32_16x16x32_bf16 v[68:71], v[144:147], v[212:215], v[68:71]
	v_mfma_f32_16x16x32_bf16 v[68:71], v[148:151], v[218:221], v[68:71]
	v_mfma_f32_16x16x32_bf16 v[112:115], v[152:155], v[160:163], v[112:115]
	v_mfma_f32_16x16x32_bf16 v[112:115], v[156:159], v[164:167], v[112:115]
	v_mfma_f32_16x16x32_bf16 v[96:99], v[152:155], v[168:171], v[96:99]
	v_mfma_f32_16x16x32_bf16 v[96:99], v[156:159], v[172:175], v[96:99]
	v_mfma_f32_16x16x32_bf16 v[80:83], v[152:155], v[204:207], v[80:83]
	v_mfma_f32_16x16x32_bf16 v[80:83], v[156:159], v[208:211], v[80:83]
	v_mfma_f32_16x16x32_bf16 v[64:67], v[152:155], v[212:215], v[64:67]
	v_mfma_f32_16x16x32_bf16 v[64:67], v[156:159], v[218:221], v[64:67]
	s_barrier
	s_add_i32 s58, s58, s50
	v_lshl_add_u64 v[198:199], s[52:53], 0, v[178:179]
	s_mov_b32 m0, s58
	ds_read_b128 v[160:163], v203 offset:16384
	ds_read_b128 v[164:167], v203 offset:17408
	ds_read_b128 v[168:171], v203 offset:18432
	ds_read_b128 v[172:175], v203 offset:19456
	ds_read_b128 v[204:207], v203 offset:20480
	ds_read_b128 v[208:211], v203 offset:21504
	ds_read_b128 v[212:215], v203 offset:22528
	ds_read_b128 v[218:221], v203 offset:23552
	global_load_lds_dwordx4 v[198:199], off
	s_add_i32 m0, s58, 0x2000
	s_add_u32 s58, s52, 0x80000
	v_lshl_add_u64 v[222:223], s[52:53], 0, v[182:183]
	s_addc_u32 s59, s53, 0
	s_add_i32 s81, s81, s50
	global_load_lds_dwordx4 v[222:223], off
	v_lshl_add_u64 v[224:225], s[58:59], 0, v[178:179]
	s_mov_b32 m0, s81
	v_lshl_add_u64 v[226:227], s[54:55], 0, v[180:181]
	global_load_lds_dwordx4 v[224:225], off
	v_lshl_add_u64 v[224:225], s[58:59], 0, v[182:183]
	s_add_i32 m0, s81, 0x2000
	s_nop 0
	global_load_lds_dwordx4 v[224:225], off
	v_lshl_add_u64 v[224:225], s[54:55], 0, v[176:177]
	s_mov_b32 m0, s76
	s_nop 0
	global_load_lds_dwordx4 v[224:225], off
	s_mov_b32 m0, s87
	s_nop 0
	global_load_lds_dwordx4 v[226:227], off
	s_waitcnt vmcnt(8)
	s_waitcnt lgkmcnt(0)
	s_barrier
	v_mfma_f32_16x16x32_bf16 v[60:63], v[128:131], v[160:163], v[60:63]
	v_mfma_f32_16x16x32_bf16 v[60:63], v[132:135], v[164:167], v[60:63]
	v_mfma_f32_16x16x32_bf16 v[44:47], v[128:131], v[168:171], v[44:47]
	v_mfma_f32_16x16x32_bf16 v[44:47], v[132:135], v[172:175], v[44:47]
	v_mfma_f32_16x16x32_bf16 v[28:31], v[128:131], v[204:207], v[28:31]
	v_mfma_f32_16x16x32_bf16 v[28:31], v[132:135], v[208:211], v[28:31]
	v_mfma_f32_16x16x32_bf16 v[12:15], v[128:131], v[212:215], v[12:15]
	v_mfma_f32_16x16x32_bf16 v[12:15], v[132:135], v[218:221], v[12:15]
	v_mfma_f32_16x16x32_bf16 v[56:59], v[136:139], v[160:163], v[56:59]
	v_mfma_f32_16x16x32_bf16 v[56:59], v[140:143], v[164:167], v[56:59]
	v_mfma_f32_16x16x32_bf16 v[40:43], v[136:139], v[168:171], v[40:43]
	v_mfma_f32_16x16x32_bf16 v[40:43], v[140:143], v[172:175], v[40:43]
	v_mfma_f32_16x16x32_bf16 v[24:27], v[136:139], v[204:207], v[24:27]
	v_mfma_f32_16x16x32_bf16 v[24:27], v[140:143], v[208:211], v[24:27]
	v_mfma_f32_16x16x32_bf16 v[8:11], v[136:139], v[212:215], v[8:11]
	v_mfma_f32_16x16x32_bf16 v[8:11], v[140:143], v[218:221], v[8:11]
	v_mfma_f32_16x16x32_bf16 v[52:55], v[144:147], v[160:163], v[52:55]
	v_mfma_f32_16x16x32_bf16 v[52:55], v[148:151], v[164:167], v[52:55]
	v_mfma_f32_16x16x32_bf16 v[36:39], v[144:147], v[168:171], v[36:39]
	v_mfma_f32_16x16x32_bf16 v[36:39], v[148:151], v[172:175], v[36:39]
	v_mfma_f32_16x16x32_bf16 v[20:23], v[144:147], v[204:207], v[20:23]
	v_mfma_f32_16x16x32_bf16 v[20:23], v[148:151], v[208:211], v[20:23]
	v_mfma_f32_16x16x32_bf16 v[4:7], v[144:147], v[212:215], v[4:7]
	v_mfma_f32_16x16x32_bf16 v[4:7], v[148:151], v[218:221], v[4:7]
	v_mfma_f32_16x16x32_bf16 v[48:51], v[152:155], v[160:163], v[48:51]
	v_mfma_f32_16x16x32_bf16 v[48:51], v[156:159], v[164:167], v[48:51]
	v_mfma_f32_16x16x32_bf16 v[32:35], v[152:155], v[168:171], v[32:35]
	v_mfma_f32_16x16x32_bf16 v[32:35], v[156:159], v[172:175], v[32:35]
	v_mfma_f32_16x16x32_bf16 v[16:19], v[152:155], v[204:207], v[16:19]
	v_mfma_f32_16x16x32_bf16 v[16:19], v[156:159], v[208:211], v[16:19]
	v_mfma_f32_16x16x32_bf16 v[0:3], v[152:155], v[212:215], v[0:3]
	v_mfma_f32_16x16x32_bf16 v[0:3], v[156:159], v[218:221], v[0:3]
	s_barrier
	s_add_i32 s58, 0, 0x18000
	s_add_i32 s59, 0, 0x1c000
	v_add_u32_e32 v140, s58, v197
	v_add_u32_e32 v156, s59, v197
	ds_read_b128 v[128:131], v140
	ds_read_b128 v[132:135], v140 offset:1024
	ds_read_b128 v[136:139], v140 offset:2048
	ds_read_b128 v[140:143], v140 offset:3072
	ds_read_b128 v[144:147], v156
	ds_read_b128 v[148:151], v156 offset:1024
	ds_read_b128 v[152:155], v156 offset:2048
	ds_read_b128 v[156:159], v156 offset:3072
	s_add_u32 s54, s54, 0x80000
	s_addc_u32 s55, s55, 0
	s_mov_b32 m0, s92
	v_lshl_add_u64 v[228:229], s[54:55], 0, v[176:177]
	ds_read_b128 v[160:163], v203 offset:32768
	ds_read_b128 v[164:167], v203 offset:33792
	ds_read_b128 v[168:171], v203 offset:34816
	ds_read_b128 v[172:175], v203 offset:35840
	ds_read_b128 v[204:207], v203 offset:36864
	ds_read_b128 v[208:211], v203 offset:37888
	ds_read_b128 v[212:215], v203 offset:38912
	ds_read_b128 v[218:221], v203 offset:39936
	global_load_lds_dwordx4 v[228:229], off
	v_lshl_add_u64 v[228:229], s[54:55], 0, v[180:181]
	s_mov_b32 m0, s93
	s_nop 0
	global_load_lds_dwordx4 v[228:229], off
	s_waitcnt vmcnt(8)
	s_waitcnt lgkmcnt(0)
	s_barrier
	v_mfma_f32_16x16x32_bf16 v[124:127], v[128:131], v[160:163], v[124:127]
	v_mfma_f32_16x16x32_bf16 v[124:127], v[132:135], v[164:167], v[124:127]
	v_mfma_f32_16x16x32_bf16 v[108:111], v[128:131], v[168:171], v[108:111]
	v_mfma_f32_16x16x32_bf16 v[108:111], v[132:135], v[172:175], v[108:111]
	v_mfma_f32_16x16x32_bf16 v[92:95], v[128:131], v[204:207], v[92:95]
	v_mfma_f32_16x16x32_bf16 v[92:95], v[132:135], v[208:211], v[92:95]
	v_mfma_f32_16x16x32_bf16 v[76:79], v[128:131], v[212:215], v[76:79]
	v_mfma_f32_16x16x32_bf16 v[76:79], v[132:135], v[218:221], v[76:79]
	v_mfma_f32_16x16x32_bf16 v[120:123], v[136:139], v[160:163], v[120:123]
	v_mfma_f32_16x16x32_bf16 v[120:123], v[140:143], v[164:167], v[120:123]
	v_mfma_f32_16x16x32_bf16 v[104:107], v[136:139], v[168:171], v[104:107]
	v_mfma_f32_16x16x32_bf16 v[104:107], v[140:143], v[172:175], v[104:107]
	v_mfma_f32_16x16x32_bf16 v[88:91], v[136:139], v[204:207], v[88:91]
	v_mfma_f32_16x16x32_bf16 v[88:91], v[140:143], v[208:211], v[88:91]
	v_mfma_f32_16x16x32_bf16 v[72:75], v[136:139], v[212:215], v[72:75]
	v_mfma_f32_16x16x32_bf16 v[72:75], v[140:143], v[218:221], v[72:75]
	v_mfma_f32_16x16x32_bf16 v[116:119], v[144:147], v[160:163], v[116:119]
	v_mfma_f32_16x16x32_bf16 v[116:119], v[148:151], v[164:167], v[116:119]
	v_mfma_f32_16x16x32_bf16 v[100:103], v[144:147], v[168:171], v[100:103]
	v_mfma_f32_16x16x32_bf16 v[100:103], v[148:151], v[172:175], v[100:103]
	v_mfma_f32_16x16x32_bf16 v[84:87], v[144:147], v[204:207], v[84:87]
	v_mfma_f32_16x16x32_bf16 v[84:87], v[148:151], v[208:211], v[84:87]
	v_mfma_f32_16x16x32_bf16 v[68:71], v[144:147], v[212:215], v[68:71]
	v_mfma_f32_16x16x32_bf16 v[68:71], v[148:151], v[218:221], v[68:71]
	v_mfma_f32_16x16x32_bf16 v[112:115], v[152:155], v[160:163], v[112:115]
	v_mfma_f32_16x16x32_bf16 v[112:115], v[156:159], v[164:167], v[112:115]
	v_mfma_f32_16x16x32_bf16 v[96:99], v[152:155], v[168:171], v[96:99]
	v_mfma_f32_16x16x32_bf16 v[96:99], v[156:159], v[172:175], v[96:99]
	v_mfma_f32_16x16x32_bf16 v[80:83], v[152:155], v[204:207], v[80:83]
	v_mfma_f32_16x16x32_bf16 v[80:83], v[156:159], v[208:211], v[80:83]
	v_mfma_f32_16x16x32_bf16 v[64:67], v[152:155], v[212:215], v[64:67]
	v_mfma_f32_16x16x32_bf16 v[64:67], v[156:159], v[218:221], v[64:67]
	s_barrier
	s_add_i32 s54, s58, s50
	v_lshl_add_u64 v[198:199], v[198:199], 0, s[60:61]
	s_mov_b32 m0, s54
	ds_read_b128 v[160:163], v203 offset:49152
	ds_read_b128 v[164:167], v203 offset:50176
	ds_read_b128 v[168:171], v203 offset:51200
	ds_read_b128 v[172:175], v203 offset:52224
	ds_read_b128 v[204:207], v203 offset:53248
	ds_read_b128 v[208:211], v203 offset:54272
	ds_read_b128 v[212:215], v203 offset:55296
	ds_read_b128 v[218:221], v203 offset:56320
	global_load_lds_dwordx4 v[198:199], off
	s_add_i32 m0, s54, 0x2000
	s_add_u32 s52, s52, 0x80080
	v_lshl_add_u64 v[198:199], v[222:223], 0, s[60:61]
	s_addc_u32 s53, s53, 0
	s_add_i32 s54, s59, s50
	global_load_lds_dwordx4 v[198:199], off
	v_lshl_add_u64 v[198:199], s[52:53], 0, v[178:179]
	s_mov_b32 m0, s54
	s_nop 0
	global_load_lds_dwordx4 v[198:199], off
	v_lshl_add_u64 v[198:199], s[52:53], 0, v[182:183]
	s_add_i32 m0, s54, 0x2000
	s_nop 0
	global_load_lds_dwordx4 v[198:199], off
	v_lshl_add_u64 v[198:199], v[224:225], 0, s[60:61]
	s_mov_b32 m0, s94
	s_nop 0
	global_load_lds_dwordx4 v[198:199], off
	v_lshl_add_u64 v[198:199], v[226:227], 0, s[60:61]
	s_mov_b32 m0, s95
	s_nop 0
	global_load_lds_dwordx4 v[198:199], off
	s_waitcnt vmcnt(8)
	s_waitcnt lgkmcnt(0)
	s_barrier
	v_mfma_f32_16x16x32_bf16 v[60:63], v[128:131], v[160:163], v[60:63]
	v_mfma_f32_16x16x32_bf16 v[60:63], v[132:135], v[164:167], v[60:63]
	v_mfma_f32_16x16x32_bf16 v[44:47], v[128:131], v[168:171], v[44:47]
	v_mfma_f32_16x16x32_bf16 v[44:47], v[132:135], v[172:175], v[44:47]
	v_mfma_f32_16x16x32_bf16 v[28:31], v[128:131], v[204:207], v[28:31]
	v_mfma_f32_16x16x32_bf16 v[28:31], v[132:135], v[208:211], v[28:31]
	v_mfma_f32_16x16x32_bf16 v[12:15], v[128:131], v[212:215], v[12:15]
	v_mfma_f32_16x16x32_bf16 v[12:15], v[132:135], v[218:221], v[12:15]
	v_mfma_f32_16x16x32_bf16 v[56:59], v[136:139], v[160:163], v[56:59]
	v_mfma_f32_16x16x32_bf16 v[56:59], v[140:143], v[164:167], v[56:59]
	v_mfma_f32_16x16x32_bf16 v[40:43], v[136:139], v[168:171], v[40:43]
	v_mfma_f32_16x16x32_bf16 v[40:43], v[140:143], v[172:175], v[40:43]
	v_mfma_f32_16x16x32_bf16 v[24:27], v[136:139], v[204:207], v[24:27]
	v_mfma_f32_16x16x32_bf16 v[24:27], v[140:143], v[208:211], v[24:27]
	v_mfma_f32_16x16x32_bf16 v[8:11], v[136:139], v[212:215], v[8:11]
	v_mfma_f32_16x16x32_bf16 v[8:11], v[140:143], v[218:221], v[8:11]
	v_mfma_f32_16x16x32_bf16 v[52:55], v[144:147], v[160:163], v[52:55]
	v_mfma_f32_16x16x32_bf16 v[52:55], v[148:151], v[164:167], v[52:55]
	v_mfma_f32_16x16x32_bf16 v[36:39], v[144:147], v[168:171], v[36:39]
	v_mfma_f32_16x16x32_bf16 v[36:39], v[148:151], v[172:175], v[36:39]
	v_mfma_f32_16x16x32_bf16 v[20:23], v[144:147], v[204:207], v[20:23]
	v_mfma_f32_16x16x32_bf16 v[20:23], v[148:151], v[208:211], v[20:23]
	v_mfma_f32_16x16x32_bf16 v[4:7], v[144:147], v[212:215], v[4:7]
	v_mfma_f32_16x16x32_bf16 v[4:7], v[148:151], v[218:221], v[4:7]
	v_mfma_f32_16x16x32_bf16 v[48:51], v[152:155], v[160:163], v[48:51]
	v_mfma_f32_16x16x32_bf16 v[48:51], v[156:159], v[164:167], v[48:51]
	v_mfma_f32_16x16x32_bf16 v[32:35], v[152:155], v[168:171], v[32:35]
	v_mfma_f32_16x16x32_bf16 v[32:35], v[156:159], v[172:175], v[32:35]
	v_mfma_f32_16x16x32_bf16 v[16:19], v[152:155], v[204:207], v[16:19]
	v_mfma_f32_16x16x32_bf16 v[16:19], v[156:159], v[208:211], v[16:19]
	v_mfma_f32_16x16x32_bf16 v[0:3], v[152:155], v[212:215], v[0:3]
	v_mfma_f32_16x16x32_bf16 v[0:3], v[156:159], v[218:221], v[0:3]
	s_barrier
	s_add_i32 vcc_hi, vcc_hi, 2
	s_add_u32 s88, s88, 0x100
	s_addc_u32 s89, s89, 0
	s_add_u32 s90, s90, 0x100
	s_addc_u32 s91, s91, 0
	s_cmp_gt_u32 vcc_hi, 29
	s_cbranch_scc0 .LBB0_827
	s_and_b64 vcc, exec, s[38:39]
	s_cbranch_vccz .LBB0_830
	s_barrier

.LBB0_1009:
	s_add_u32 s18, s16, 0x100
	s_addc_u32 s19, s17, 0
	s_add_i32 s2, 0, 0x10000
	s_cmp_eq_u32 s93, 4
	s_cselect_b32 s53, s13, s19
	s_cselect_b32 s52, s12, s18
	s_cselect_b32 s23, s15, s9
	s_cselect_b32 s22, s14, s7
	s_add_i32 s58, 0, 0x14000
	v_add_u32_e32 v156, s2, v142
	v_add_u32_e32 v172, s58, v142
	ds_read_b128 v[144:147], v156
	ds_read_b128 v[148:151], v156 offset:1024
	ds_read_b128 v[152:155], v156 offset:2048
	ds_read_b128 v[156:159], v156 offset:3072
	ds_read_b128 v[160:163], v172
	ds_read_b128 v[164:167], v172 offset:1024
	ds_read_b128 v[168:171], v172 offset:2048
	ds_read_b128 v[172:175], v172 offset:3072
	v_lshl_add_u64 v[208:209], s[16:17], 0, v[136:137]
	s_add_i32 m0, s76, 0xc000
	ds_read_b128 v[176:179], v143
	ds_read_b128 v[180:183], v143 offset:1024
	ds_read_b128 v[184:187], v143 offset:2048
	ds_read_b128 v[188:191], v143 offset:3072
	ds_read_b128 v[192:195], v143 offset:4096
	ds_read_b128 v[196:199], v143 offset:5120
	ds_read_b128 v[200:203], v143 offset:6144
	ds_read_b128 v[204:207], v143 offset:7168
	global_load_lds_dwordx4 v[208:209], off
	v_lshl_add_u64 v[208:209], s[16:17], 0, v[138:139]
	s_add_i32 m0, s76, 0xe000
	s_nop 0
	global_load_lds_dwordx4 v[208:209], off
	s_waitcnt vmcnt(8)
	s_waitcnt lgkmcnt(0)
	s_barrier
	v_mfma_f32_16x16x32_bf16 v[124:127], v[144:147], v[176:179], v[124:127]
	v_mfma_f32_16x16x32_bf16 v[124:127], v[148:151], v[180:183], v[124:127]
	v_mfma_f32_16x16x32_bf16 v[116:119], v[144:147], v[184:187], v[116:119]
	v_mfma_f32_16x16x32_bf16 v[116:119], v[148:151], v[188:191], v[116:119]
	v_mfma_f32_16x16x32_bf16 v[104:107], v[144:147], v[192:195], v[104:107]
	v_mfma_f32_16x16x32_bf16 v[104:107], v[148:151], v[196:199], v[104:107]
	v_mfma_f32_16x16x32_bf16 v[88:91], v[144:147], v[200:203], v[88:91]
	v_mfma_f32_16x16x32_bf16 v[88:91], v[148:151], v[204:207], v[88:91]
	v_mfma_f32_16x16x32_bf16 v[120:123], v[152:155], v[176:179], v[120:123]
	v_mfma_f32_16x16x32_bf16 v[120:123], v[156:159], v[180:183], v[120:123]
	v_mfma_f32_16x16x32_bf16 v[112:115], v[152:155], v[184:187], v[112:115]
	v_mfma_f32_16x16x32_bf16 v[112:115], v[156:159], v[188:191], v[112:115]
	v_mfma_f32_16x16x32_bf16 v[96:99], v[152:155], v[192:195], v[96:99]
	v_mfma_f32_16x16x32_bf16 v[96:99], v[156:159], v[196:199], v[96:99]
	v_mfma_f32_16x16x32_bf16 v[80:83], v[152:155], v[200:203], v[80:83]
	v_mfma_f32_16x16x32_bf16 v[80:83], v[156:159], v[204:207], v[80:83]
	v_mfma_f32_16x16x32_bf16 v[108:111], v[160:163], v[176:179], v[108:111]
	v_mfma_f32_16x16x32_bf16 v[108:111], v[164:167], v[180:183], v[108:111]
	v_mfma_f32_16x16x32_bf16 v[92:95], v[160:163], v[184:187], v[92:95]
	v_mfma_f32_16x16x32_bf16 v[92:95], v[164:167], v[188:191], v[92:95]
	v_mfma_f32_16x16x32_bf16 v[76:79], v[160:163], v[192:195], v[76:79]
	v_mfma_f32_16x16x32_bf16 v[76:79], v[164:167], v[196:199], v[76:79]
	v_mfma_f32_16x16x32_bf16 v[68:71], v[160:163], v[200:203], v[68:71]
	v_mfma_f32_16x16x32_bf16 v[68:71], v[164:167], v[204:207], v[68:71]
	v_mfma_f32_16x16x32_bf16 v[100:103], v[168:171], v[176:179], v[100:103]
	v_mfma_f32_16x16x32_bf16 v[100:103], v[172:175], v[180:183], v[100:103]
	v_mfma_f32_16x16x32_bf16 v[84:87], v[168:171], v[184:187], v[84:87]
	v_mfma_f32_16x16x32_bf16 v[84:87], v[172:175], v[188:191], v[84:87]
	v_mfma_f32_16x16x32_bf16 v[72:75], v[168:171], v[192:195], v[72:75]
	v_mfma_f32_16x16x32_bf16 v[72:75], v[172:175], v[196:199], v[72:75]
	v_mfma_f32_16x16x32_bf16 v[64:67], v[168:171], v[200:203], v[64:67]
	v_mfma_f32_16x16x32_bf16 v[64:67], v[172:175], v[204:207], v[64:67]
	s_barrier
	s_add_i32 s2, s2, s50
	v_lshl_add_u64 v[208:209], s[22:23], 0, v[216:217]
	s_mov_b32 m0, s2
	ds_read_b128 v[176:179], v143 offset:16384
	ds_read_b128 v[180:183], v143 offset:17408
	ds_read_b128 v[184:187], v143 offset:18432
	ds_read_b128 v[188:191], v143 offset:19456
	ds_read_b128 v[192:195], v143 offset:20480
	ds_read_b128 v[196:199], v143 offset:21504
	ds_read_b128 v[200:203], v143 offset:22528
	ds_read_b128 v[204:207], v143 offset:23552
	global_load_lds_dwordx4 v[208:209], off
	s_add_i32 m0, s2, 0x2000
	s_add_u32 s2, s22, 0x20000
	v_lshl_add_u64 v[210:211], s[22:23], 0, v[128:129]
	s_addc_u32 s3, s23, 0
	s_add_i32 s16, s58, s50
	global_load_lds_dwordx4 v[210:211], off
	v_lshl_add_u64 v[212:213], s[2:3], 0, v[216:217]
	s_mov_b32 m0, s16
	v_lshl_add_u64 v[214:215], s[52:53], 0, v[130:131]
	global_load_lds_dwordx4 v[212:213], off
	v_lshl_add_u64 v[212:213], s[2:3], 0, v[128:129]
	s_add_i32 m0, s16, 0x2000
	s_nop 0
	global_load_lds_dwordx4 v[212:213], off
	v_lshl_add_u64 v[212:213], s[52:53], 0, v[132:133]
	s_mov_b32 m0, s76
	s_nop 0
	global_load_lds_dwordx4 v[212:213], off
	s_mov_b32 m0, s72
	s_nop 0
	global_load_lds_dwordx4 v[214:215], off
	s_waitcnt vmcnt(8)
	s_waitcnt lgkmcnt(0)
	s_barrier
	v_mfma_f32_16x16x32_bf16 v[60:63], v[144:147], v[176:179], v[60:63]
	v_mfma_f32_16x16x32_bf16 v[60:63], v[148:151], v[180:183], v[60:63]
	v_mfma_f32_16x16x32_bf16 v[52:55], v[144:147], v[184:187], v[52:55]
	v_mfma_f32_16x16x32_bf16 v[52:55], v[148:151], v[188:191], v[52:55]
	v_mfma_f32_16x16x32_bf16 v[36:39], v[144:147], v[192:195], v[36:39]
	v_mfma_f32_16x16x32_bf16 v[36:39], v[148:151], v[196:199], v[36:39]
	v_mfma_f32_16x16x32_bf16 v[20:23], v[144:147], v[200:203], v[20:23]
	v_mfma_f32_16x16x32_bf16 v[20:23], v[148:151], v[204:207], v[20:23]
	v_mfma_f32_16x16x32_bf16 v[56:59], v[152:155], v[176:179], v[56:59]
	v_mfma_f32_16x16x32_bf16 v[56:59], v[156:159], v[180:183], v[56:59]
	v_mfma_f32_16x16x32_bf16 v[48:51], v[152:155], v[184:187], v[48:51]
	v_mfma_f32_16x16x32_bf16 v[48:51], v[156:159], v[188:191], v[48:51]
	v_mfma_f32_16x16x32_bf16 v[32:35], v[152:155], v[192:195], v[32:35]
	v_mfma_f32_16x16x32_bf16 v[32:35], v[156:159], v[196:199], v[32:35]
	v_mfma_f32_16x16x32_bf16 v[16:19], v[152:155], v[200:203], v[16:19]
	v_mfma_f32_16x16x32_bf16 v[16:19], v[156:159], v[204:207], v[16:19]
	v_mfma_f32_16x16x32_bf16 v[44:47], v[160:163], v[176:179], v[44:47]
	v_mfma_f32_16x16x32_bf16 v[44:47], v[164:167], v[180:183], v[44:47]
	v_mfma_f32_16x16x32_bf16 v[28:31], v[160:163], v[184:187], v[28:31]
	v_mfma_f32_16x16x32_bf16 v[28:31], v[164:167], v[188:191], v[28:31]
	v_mfma_f32_16x16x32_bf16 v[12:15], v[160:163], v[192:195], v[12:15]
	v_mfma_f32_16x16x32_bf16 v[12:15], v[164:167], v[196:199], v[12:15]
	v_mfma_f32_16x16x32_bf16 v[4:7], v[160:163], v[200:203], v[4:7]
	v_mfma_f32_16x16x32_bf16 v[4:7], v[164:167], v[204:207], v[4:7]
	v_mfma_f32_16x16x32_bf16 v[40:43], v[168:171], v[176:179], v[40:43]
	v_mfma_f32_16x16x32_bf16 v[40:43], v[172:175], v[180:183], v[40:43]
	v_mfma_f32_16x16x32_bf16 v[24:27], v[168:171], v[184:187], v[24:27]
	v_mfma_f32_16x16x32_bf16 v[24:27], v[172:175], v[188:191], v[24:27]
	v_mfma_f32_16x16x32_bf16 v[8:11], v[168:171], v[192:195], v[8:11]
	v_mfma_f32_16x16x32_bf16 v[8:11], v[172:175], v[196:199], v[8:11]
	v_mfma_f32_16x16x32_bf16 v[0:3], v[168:171], v[200:203], v[0:3]
	v_mfma_f32_16x16x32_bf16 v[0:3], v[172:175], v[204:207], v[0:3]
	s_barrier
	s_add_i32 s16, 0, 0x18000
	s_add_i32 s17, 0, 0x1c000
	v_add_u32_e32 v156, s16, v142
	v_add_u32_e32 v172, s17, v142
	ds_read_b128 v[144:147], v156
	ds_read_b128 v[148:151], v156 offset:1024
	ds_read_b128 v[152:155], v156 offset:2048
	ds_read_b128 v[156:159], v156 offset:3072
	ds_read_b128 v[160:163], v172
	ds_read_b128 v[164:167], v172 offset:1024
	ds_read_b128 v[168:171], v172 offset:2048
	ds_read_b128 v[172:175], v172 offset:3072
	s_add_u32 s2, s52, 0x30000
	s_addc_u32 s3, s53, 0
	s_mov_b32 m0, s74
	v_lshl_add_u64 v[218:219], s[2:3], 0, v[132:133]
	ds_read_b128 v[176:179], v143 offset:32768
	ds_read_b128 v[180:183], v143 offset:33792
	ds_read_b128 v[184:187], v143 offset:34816
	ds_read_b128 v[188:191], v143 offset:35840
	ds_read_b128 v[192:195], v143 offset:36864
	ds_read_b128 v[196:199], v143 offset:37888
	ds_read_b128 v[200:203], v143 offset:38912
	ds_read_b128 v[204:207], v143 offset:39936
	global_load_lds_dwordx4 v[218:219], off
	v_lshl_add_u64 v[218:219], s[2:3], 0, v[130:131]
	s_mov_b32 m0, s85
	s_nop 0
	global_load_lds_dwordx4 v[218:219], off
	s_waitcnt vmcnt(8)
	s_waitcnt lgkmcnt(0)
	s_barrier
	v_mfma_f32_16x16x32_bf16 v[124:127], v[144:147], v[176:179], v[124:127]
	v_mfma_f32_16x16x32_bf16 v[124:127], v[148:151], v[180:183], v[124:127]
	v_mfma_f32_16x16x32_bf16 v[116:119], v[144:147], v[184:187], v[116:119]
	v_mfma_f32_16x16x32_bf16 v[116:119], v[148:151], v[188:191], v[116:119]
	v_mfma_f32_16x16x32_bf16 v[104:107], v[144:147], v[192:195], v[104:107]
	v_mfma_f32_16x16x32_bf16 v[104:107], v[148:151], v[196:199], v[104:107]
	v_mfma_f32_16x16x32_bf16 v[88:91], v[144:147], v[200:203], v[88:91]
	v_mfma_f32_16x16x32_bf16 v[88:91], v[148:151], v[204:207], v[88:91]
	v_mfma_f32_16x16x32_bf16 v[120:123], v[152:155], v[176:179], v[120:123]
	v_mfma_f32_16x16x32_bf16 v[120:123], v[156:159], v[180:183], v[120:123]
	v_mfma_f32_16x16x32_bf16 v[112:115], v[152:155], v[184:187], v[112:115]
	v_mfma_f32_16x16x32_bf16 v[112:115], v[156:159], v[188:191], v[112:115]
	v_mfma_f32_16x16x32_bf16 v[96:99], v[152:155], v[192:195], v[96:99]
	v_mfma_f32_16x16x32_bf16 v[96:99], v[156:159], v[196:199], v[96:99]
	v_mfma_f32_16x16x32_bf16 v[80:83], v[152:155], v[200:203], v[80:83]
	v_mfma_f32_16x16x32_bf16 v[80:83], v[156:159], v[204:207], v[80:83]
	v_mfma_f32_16x16x32_bf16 v[108:111], v[160:163], v[176:179], v[108:111]
	v_mfma_f32_16x16x32_bf16 v[108:111], v[164:167], v[180:183], v[108:111]
	v_mfma_f32_16x16x32_bf16 v[92:95], v[160:163], v[184:187], v[92:95]
	v_mfma_f32_16x16x32_bf16 v[92:95], v[164:167], v[188:191], v[92:95]
	v_mfma_f32_16x16x32_bf16 v[76:79], v[160:163], v[192:195], v[76:79]
	v_mfma_f32_16x16x32_bf16 v[76:79], v[164:167], v[196:199], v[76:79]
	v_mfma_f32_16x16x32_bf16 v[68:71], v[160:163], v[200:203], v[68:71]
	v_mfma_f32_16x16x32_bf16 v[68:71], v[164:167], v[204:207], v[68:71]
	v_mfma_f32_16x16x32_bf16 v[100:103], v[168:171], v[176:179], v[100:103]
	v_mfma_f32_16x16x32_bf16 v[100:103], v[172:175], v[180:183], v[100:103]
	v_mfma_f32_16x16x32_bf16 v[84:87], v[168:171], v[184:187], v[84:87]
	v_mfma_f32_16x16x32_bf16 v[84:87], v[172:175], v[188:191], v[84:87]
	v_mfma_f32_16x16x32_bf16 v[72:75], v[168:171], v[192:195], v[72:75]
	v_mfma_f32_16x16x32_bf16 v[72:75], v[172:175], v[196:199], v[72:75]
	v_mfma_f32_16x16x32_bf16 v[64:67], v[168:171], v[200:203], v[64:67]
	v_mfma_f32_16x16x32_bf16 v[64:67], v[172:175], v[204:207], v[64:67]
	s_barrier
	s_add_i32 s2, s16, s50
	v_lshl_add_u64 v[208:209], v[208:209], 0, s[60:61]
	s_mov_b32 m0, s2
	ds_read_b128 v[176:179], v143 offset:49152
	ds_read_b128 v[180:183], v143 offset:50176
	ds_read_b128 v[184:187], v143 offset:51200
	ds_read_b128 v[188:191], v143 offset:52224
	ds_read_b128 v[192:195], v143 offset:53248
	ds_read_b128 v[196:199], v143 offset:54272
	ds_read_b128 v[200:203], v143 offset:55296
	ds_read_b128 v[204:207], v143 offset:56320
	global_load_lds_dwordx4 v[208:209], off
	s_add_i32 m0, s2, 0x2000
	s_add_u32 s2, s22, 0x20080
	v_lshl_add_u64 v[208:209], v[210:211], 0, s[60:61]
	s_addc_u32 s3, s23, 0
	s_add_i32 s16, s17, s50
	global_load_lds_dwordx4 v[208:209], off
	v_lshl_add_u64 v[208:209], s[2:3], 0, v[216:217]
	s_mov_b32 m0, s16
	s_nop 0
	global_load_lds_dwordx4 v[208:209], off
	v_lshl_add_u64 v[208:209], s[2:3], 0, v[128:129]
	s_add_i32 m0, s16, 0x2000
	s_nop 0
	global_load_lds_dwordx4 v[208:209], off
	v_lshl_add_u64 v[208:209], v[212:213], 0, s[60:61]
	s_mov_b32 m0, s89
	s_nop 0
	global_load_lds_dwordx4 v[208:209], off
	v_lshl_add_u64 v[208:209], v[214:215], 0, s[60:61]
	s_mov_b32 m0, s90
	s_nop 0
	global_load_lds_dwordx4 v[208:209], off
	s_waitcnt vmcnt(8)
	s_waitcnt lgkmcnt(0)
	s_barrier
	v_mfma_f32_16x16x32_bf16 v[60:63], v[144:147], v[176:179], v[60:63]
	v_mfma_f32_16x16x32_bf16 v[60:63], v[148:151], v[180:183], v[60:63]
	v_mfma_f32_16x16x32_bf16 v[52:55], v[144:147], v[184:187], v[52:55]
	v_mfma_f32_16x16x32_bf16 v[52:55], v[148:151], v[188:191], v[52:55]
	v_mfma_f32_16x16x32_bf16 v[36:39], v[144:147], v[192:195], v[36:39]
	v_mfma_f32_16x16x32_bf16 v[36:39], v[148:151], v[196:199], v[36:39]
	v_mfma_f32_16x16x32_bf16 v[20:23], v[144:147], v[200:203], v[20:23]
	v_mfma_f32_16x16x32_bf16 v[20:23], v[148:151], v[204:207], v[20:23]
	v_mfma_f32_16x16x32_bf16 v[56:59], v[152:155], v[176:179], v[56:59]
	v_mfma_f32_16x16x32_bf16 v[56:59], v[156:159], v[180:183], v[56:59]
	v_mfma_f32_16x16x32_bf16 v[48:51], v[152:155], v[184:187], v[48:51]
	v_mfma_f32_16x16x32_bf16 v[48:51], v[156:159], v[188:191], v[48:51]
	v_mfma_f32_16x16x32_bf16 v[32:35], v[152:155], v[192:195], v[32:35]
	v_mfma_f32_16x16x32_bf16 v[32:35], v[156:159], v[196:199], v[32:35]
	v_mfma_f32_16x16x32_bf16 v[16:19], v[152:155], v[200:203], v[16:19]
	v_mfma_f32_16x16x32_bf16 v[16:19], v[156:159], v[204:207], v[16:19]
	v_mfma_f32_16x16x32_bf16 v[44:47], v[160:163], v[176:179], v[44:47]
	v_mfma_f32_16x16x32_bf16 v[44:47], v[164:167], v[180:183], v[44:47]
	v_mfma_f32_16x16x32_bf16 v[28:31], v[160:163], v[184:187], v[28:31]
	v_mfma_f32_16x16x32_bf16 v[28:31], v[164:167], v[188:191], v[28:31]
	v_mfma_f32_16x16x32_bf16 v[12:15], v[160:163], v[192:195], v[12:15]
	v_mfma_f32_16x16x32_bf16 v[12:15], v[164:167], v[196:199], v[12:15]
	v_mfma_f32_16x16x32_bf16 v[4:7], v[160:163], v[200:203], v[4:7]
	v_mfma_f32_16x16x32_bf16 v[4:7], v[164:167], v[204:207], v[4:7]
	v_mfma_f32_16x16x32_bf16 v[40:43], v[168:171], v[176:179], v[40:43]
	v_mfma_f32_16x16x32_bf16 v[40:43], v[172:175], v[180:183], v[40:43]
	v_mfma_f32_16x16x32_bf16 v[24:27], v[168:171], v[184:187], v[24:27]
	v_mfma_f32_16x16x32_bf16 v[24:27], v[172:175], v[188:191], v[24:27]
	v_mfma_f32_16x16x32_bf16 v[8:11], v[168:171], v[192:195], v[8:11]
	v_mfma_f32_16x16x32_bf16 v[8:11], v[172:175], v[196:199], v[8:11]
	v_mfma_f32_16x16x32_bf16 v[0:3], v[168:171], v[200:203], v[0:3]
	v_mfma_f32_16x16x32_bf16 v[0:3], v[172:175], v[204:207], v[0:3]
	s_barrier
	s_add_i32 s93, s93, 2
	s_add_u32 s7, s7, 0x100
	s_addc_u32 s9, s9, 0
	s_cmp_gt_u32 s93, 5
	s_mov_b64 s[16:17], s[18:19]
	s_cbranch_scc0 .LBB0_1009
	s_and_b64 vcc, exec, s[38:39]
	s_cbranch_vccz .LBB0_1012
	s_barrier

.LBB0_1326:
	s_add_u32 s16, s14, 0x100
	s_addc_u32 s17, s15, 0
	s_add_i32 s2, 0, 0x10000
	s_cmp_eq_u32 s95, 8
	s_cselect_b32 s23, s11, s17
	s_cselect_b32 s22, s10, s16
	v_add_u32_e32 v140, s2, v143
	s_cselect_b32 s19, s13, s94
	s_cselect_b32 s18, s12, s74
	s_add_i32 s58, 0, 0x14000
	ds_read_b128 v[146:149], v140
	ds_read_b128 v[150:153], v140 offset:1024
	ds_read_b128 v[154:157], v140 offset:2048
	ds_read_b128 v[158:161], v140 offset:3072
	v_add_u32_e32 v140, s58, v143
	ds_read_b128 v[162:165], v140
	ds_read_b128 v[166:169], v140 offset:1024
	ds_read_b128 v[170:173], v140 offset:2048
	ds_read_b128 v[174:177], v140 offset:3072
	v_lshl_add_u64 v[140:141], s[14:15], 0, v[136:137]
	s_add_i32 m0, s76, 0xc000
	ds_read_b128 v[178:181], v145
	ds_read_b128 v[182:185], v145 offset:1024
	ds_read_b128 v[186:189], v145 offset:2048
	ds_read_b128 v[190:193], v145 offset:3072
	ds_read_b128 v[194:197], v145 offset:4096
	ds_read_b128 v[198:201], v145 offset:5120
	ds_read_b128 v[202:205], v145 offset:6144
	ds_read_b128 v[206:209], v145 offset:7168
	global_load_lds_dwordx4 v[140:141], off
	v_lshl_add_u64 v[140:141], s[14:15], 0, v[138:139]
	s_add_i32 m0, s76, 0xe000
	s_nop 0
	global_load_lds_dwordx4 v[140:141], off
	s_waitcnt vmcnt(8)
	s_waitcnt lgkmcnt(0)
	s_barrier
	v_mfma_f32_16x16x32_bf16 v[124:127], v[146:149], v[178:181], v[124:127]
	v_mfma_f32_16x16x32_bf16 v[124:127], v[150:153], v[182:185], v[124:127]
	v_mfma_f32_16x16x32_bf16 v[108:111], v[146:149], v[186:189], v[108:111]
	v_mfma_f32_16x16x32_bf16 v[108:111], v[150:153], v[190:193], v[108:111]
	v_mfma_f32_16x16x32_bf16 v[92:95], v[146:149], v[194:197], v[92:95]
	v_mfma_f32_16x16x32_bf16 v[92:95], v[150:153], v[198:201], v[92:95]
	v_mfma_f32_16x16x32_bf16 v[76:79], v[146:149], v[202:205], v[76:79]
	v_mfma_f32_16x16x32_bf16 v[76:79], v[150:153], v[206:209], v[76:79]
	v_mfma_f32_16x16x32_bf16 v[120:123], v[154:157], v[178:181], v[120:123]
	v_mfma_f32_16x16x32_bf16 v[120:123], v[158:161], v[182:185], v[120:123]
	v_mfma_f32_16x16x32_bf16 v[104:107], v[154:157], v[186:189], v[104:107]
	v_mfma_f32_16x16x32_bf16 v[104:107], v[158:161], v[190:193], v[104:107]
	v_mfma_f32_16x16x32_bf16 v[88:91], v[154:157], v[194:197], v[88:91]
	v_mfma_f32_16x16x32_bf16 v[88:91], v[158:161], v[198:201], v[88:91]
	v_mfma_f32_16x16x32_bf16 v[72:75], v[154:157], v[202:205], v[72:75]
	v_mfma_f32_16x16x32_bf16 v[72:75], v[158:161], v[206:209], v[72:75]
	v_mfma_f32_16x16x32_bf16 v[116:119], v[162:165], v[178:181], v[116:119]
	v_mfma_f32_16x16x32_bf16 v[116:119], v[166:169], v[182:185], v[116:119]
	v_mfma_f32_16x16x32_bf16 v[100:103], v[162:165], v[186:189], v[100:103]
	v_mfma_f32_16x16x32_bf16 v[100:103], v[166:169], v[190:193], v[100:103]
	v_mfma_f32_16x16x32_bf16 v[84:87], v[162:165], v[194:197], v[84:87]
	v_mfma_f32_16x16x32_bf16 v[84:87], v[166:169], v[198:201], v[84:87]
	v_mfma_f32_16x16x32_bf16 v[68:71], v[162:165], v[202:205], v[68:71]
	v_mfma_f32_16x16x32_bf16 v[68:71], v[166:169], v[206:209], v[68:71]
	v_mfma_f32_16x16x32_bf16 v[112:115], v[170:173], v[178:181], v[112:115]
	v_mfma_f32_16x16x32_bf16 v[112:115], v[174:177], v[182:185], v[112:115]
	v_mfma_f32_16x16x32_bf16 v[96:99], v[170:173], v[186:189], v[96:99]
	v_mfma_f32_16x16x32_bf16 v[96:99], v[174:177], v[190:193], v[96:99]
	v_mfma_f32_16x16x32_bf16 v[80:83], v[170:173], v[194:197], v[80:83]
	v_mfma_f32_16x16x32_bf16 v[80:83], v[174:177], v[198:201], v[80:83]
	v_mfma_f32_16x16x32_bf16 v[64:67], v[170:173], v[202:205], v[64:67]
	v_mfma_f32_16x16x32_bf16 v[64:67], v[174:177], v[206:209], v[64:67]
	s_barrier
	s_add_i32 s2, s2, s50
	v_lshl_add_u64 v[140:141], s[18:19], 0, v[132:133]
	s_mov_b32 m0, s2
	ds_read_b128 v[178:181], v145 offset:16384
	ds_read_b128 v[182:185], v145 offset:17408
	ds_read_b128 v[186:189], v145 offset:18432
	ds_read_b128 v[190:193], v145 offset:19456
	ds_read_b128 v[194:197], v145 offset:20480
	ds_read_b128 v[198:201], v145 offset:21504
	ds_read_b128 v[202:205], v145 offset:22528
	ds_read_b128 v[206:209], v145 offset:23552
	global_load_lds_dwordx4 v[140:141], off
	s_add_i32 m0, s2, 0x2000
	s_add_u32 s2, s18, 0x30000
	v_lshl_add_u64 v[210:211], s[18:19], 0, v[128:129]
	s_addc_u32 s3, s19, 0
	s_add_i32 s14, s58, s50
	global_load_lds_dwordx4 v[210:211], off
	v_lshl_add_u64 v[212:213], s[2:3], 0, v[132:133]
	s_mov_b32 m0, s14
	v_lshl_add_u64 v[214:215], s[22:23], 0, v[130:131]
	global_load_lds_dwordx4 v[212:213], off
	v_lshl_add_u64 v[212:213], s[2:3], 0, v[128:129]
	s_add_i32 m0, s14, 0x2000
	s_nop 0
	global_load_lds_dwordx4 v[212:213], off
	v_lshl_add_u64 v[212:213], s[22:23], 0, v[134:135]
	s_mov_b32 m0, s76
	s_nop 0
	global_load_lds_dwordx4 v[212:213], off
	s_mov_b32 m0, s85
	s_nop 0
	global_load_lds_dwordx4 v[214:215], off
	s_waitcnt vmcnt(8)
	s_waitcnt lgkmcnt(0)
	s_barrier
	v_mfma_f32_16x16x32_bf16 v[60:63], v[146:149], v[178:181], v[60:63]
	v_mfma_f32_16x16x32_bf16 v[60:63], v[150:153], v[182:185], v[60:63]
	v_mfma_f32_16x16x32_bf16 v[44:47], v[146:149], v[186:189], v[44:47]
	v_mfma_f32_16x16x32_bf16 v[44:47], v[150:153], v[190:193], v[44:47]
	v_mfma_f32_16x16x32_bf16 v[28:31], v[146:149], v[194:197], v[28:31]
	v_mfma_f32_16x16x32_bf16 v[28:31], v[150:153], v[198:201], v[28:31]
	v_mfma_f32_16x16x32_bf16 v[12:15], v[146:149], v[202:205], v[12:15]
	v_mfma_f32_16x16x32_bf16 v[12:15], v[150:153], v[206:209], v[12:15]
	v_mfma_f32_16x16x32_bf16 v[56:59], v[154:157], v[178:181], v[56:59]
	v_mfma_f32_16x16x32_bf16 v[56:59], v[158:161], v[182:185], v[56:59]
	v_mfma_f32_16x16x32_bf16 v[40:43], v[154:157], v[186:189], v[40:43]
	v_mfma_f32_16x16x32_bf16 v[40:43], v[158:161], v[190:193], v[40:43]
	v_mfma_f32_16x16x32_bf16 v[24:27], v[154:157], v[194:197], v[24:27]
	v_mfma_f32_16x16x32_bf16 v[24:27], v[158:161], v[198:201], v[24:27]
	v_mfma_f32_16x16x32_bf16 v[8:11], v[154:157], v[202:205], v[8:11]
	v_mfma_f32_16x16x32_bf16 v[8:11], v[158:161], v[206:209], v[8:11]
	v_mfma_f32_16x16x32_bf16 v[52:55], v[162:165], v[178:181], v[52:55]
	v_mfma_f32_16x16x32_bf16 v[52:55], v[166:169], v[182:185], v[52:55]
	v_mfma_f32_16x16x32_bf16 v[36:39], v[162:165], v[186:189], v[36:39]
	v_mfma_f32_16x16x32_bf16 v[36:39], v[166:169], v[190:193], v[36:39]
	v_mfma_f32_16x16x32_bf16 v[20:23], v[162:165], v[194:197], v[20:23]
	v_mfma_f32_16x16x32_bf16 v[20:23], v[166:169], v[198:201], v[20:23]
	v_mfma_f32_16x16x32_bf16 v[4:7], v[162:165], v[202:205], v[4:7]
	v_mfma_f32_16x16x32_bf16 v[4:7], v[166:169], v[206:209], v[4:7]
	v_mfma_f32_16x16x32_bf16 v[48:51], v[170:173], v[178:181], v[48:51]
	v_mfma_f32_16x16x32_bf16 v[48:51], v[174:177], v[182:185], v[48:51]
	v_mfma_f32_16x16x32_bf16 v[32:35], v[170:173], v[186:189], v[32:35]
	v_mfma_f32_16x16x32_bf16 v[32:35], v[174:177], v[190:193], v[32:35]
	v_mfma_f32_16x16x32_bf16 v[16:19], v[170:173], v[194:197], v[16:19]
	v_mfma_f32_16x16x32_bf16 v[16:19], v[174:177], v[198:201], v[16:19]
	v_mfma_f32_16x16x32_bf16 v[0:3], v[170:173], v[202:205], v[0:3]
	v_mfma_f32_16x16x32_bf16 v[0:3], v[174:177], v[206:209], v[0:3]
	s_barrier
	s_add_i32 s14, 0, 0x18000
	s_add_i32 s15, 0, 0x1c000
	v_add_u32_e32 v158, s14, v143
	v_add_u32_e32 v174, s15, v143
	ds_read_b128 v[146:149], v158
	ds_read_b128 v[150:153], v158 offset:1024
	ds_read_b128 v[154:157], v158 offset:2048
	ds_read_b128 v[158:161], v158 offset:3072
	ds_read_b128 v[162:165], v174
	ds_read_b128 v[166:169], v174 offset:1024
	ds_read_b128 v[170:173], v174 offset:2048
	ds_read_b128 v[174:177], v174 offset:3072
	s_add_u32 s2, s22, 0x30000
	s_addc_u32 s3, s23, 0
	s_mov_b32 m0, s86
	v_lshl_add_u64 v[218:219], s[2:3], 0, v[134:135]
	ds_read_b128 v[178:181], v145 offset:32768
	ds_read_b128 v[182:185], v145 offset:33792
	ds_read_b128 v[186:189], v145 offset:34816
	ds_read_b128 v[190:193], v145 offset:35840
	ds_read_b128 v[194:197], v145 offset:36864
	ds_read_b128 v[198:201], v145 offset:37888
	ds_read_b128 v[202:205], v145 offset:38912
	ds_read_b128 v[206:209], v145 offset:39936
	global_load_lds_dwordx4 v[218:219], off
	v_lshl_add_u64 v[218:219], s[2:3], 0, v[130:131]
	s_mov_b32 m0, s87
	s_nop 0
	global_load_lds_dwordx4 v[218:219], off
	s_waitcnt vmcnt(8)
	s_waitcnt lgkmcnt(0)
	s_barrier
	v_mfma_f32_16x16x32_bf16 v[124:127], v[146:149], v[178:181], v[124:127]
	v_mfma_f32_16x16x32_bf16 v[124:127], v[150:153], v[182:185], v[124:127]
	v_mfma_f32_16x16x32_bf16 v[108:111], v[146:149], v[186:189], v[108:111]
	v_mfma_f32_16x16x32_bf16 v[108:111], v[150:153], v[190:193], v[108:111]
	v_mfma_f32_16x16x32_bf16 v[92:95], v[146:149], v[194:197], v[92:95]
	v_mfma_f32_16x16x32_bf16 v[92:95], v[150:153], v[198:201], v[92:95]
	v_mfma_f32_16x16x32_bf16 v[76:79], v[146:149], v[202:205], v[76:79]
	v_mfma_f32_16x16x32_bf16 v[76:79], v[150:153], v[206:209], v[76:79]
	v_mfma_f32_16x16x32_bf16 v[120:123], v[154:157], v[178:181], v[120:123]
	v_mfma_f32_16x16x32_bf16 v[120:123], v[158:161], v[182:185], v[120:123]
	v_mfma_f32_16x16x32_bf16 v[104:107], v[154:157], v[186:189], v[104:107]
	v_mfma_f32_16x16x32_bf16 v[104:107], v[158:161], v[190:193], v[104:107]
	v_mfma_f32_16x16x32_bf16 v[88:91], v[154:157], v[194:197], v[88:91]
	v_mfma_f32_16x16x32_bf16 v[88:91], v[158:161], v[198:201], v[88:91]
	v_mfma_f32_16x16x32_bf16 v[72:75], v[154:157], v[202:205], v[72:75]
	v_mfma_f32_16x16x32_bf16 v[72:75], v[158:161], v[206:209], v[72:75]
	v_mfma_f32_16x16x32_bf16 v[116:119], v[162:165], v[178:181], v[116:119]
	v_mfma_f32_16x16x32_bf16 v[116:119], v[166:169], v[182:185], v[116:119]
	v_mfma_f32_16x16x32_bf16 v[100:103], v[162:165], v[186:189], v[100:103]
	v_mfma_f32_16x16x32_bf16 v[100:103], v[166:169], v[190:193], v[100:103]
	v_mfma_f32_16x16x32_bf16 v[84:87], v[162:165], v[194:197], v[84:87]
	v_mfma_f32_16x16x32_bf16 v[84:87], v[166:169], v[198:201], v[84:87]
	v_mfma_f32_16x16x32_bf16 v[68:71], v[162:165], v[202:205], v[68:71]
	v_mfma_f32_16x16x32_bf16 v[68:71], v[166:169], v[206:209], v[68:71]
	v_mfma_f32_16x16x32_bf16 v[112:115], v[170:173], v[178:181], v[112:115]
	v_mfma_f32_16x16x32_bf16 v[112:115], v[174:177], v[182:185], v[112:115]
	v_mfma_f32_16x16x32_bf16 v[96:99], v[170:173], v[186:189], v[96:99]
	v_mfma_f32_16x16x32_bf16 v[96:99], v[174:177], v[190:193], v[96:99]
	v_mfma_f32_16x16x32_bf16 v[80:83], v[170:173], v[194:197], v[80:83]
	v_mfma_f32_16x16x32_bf16 v[80:83], v[174:177], v[198:201], v[80:83]
	v_mfma_f32_16x16x32_bf16 v[64:67], v[170:173], v[202:205], v[64:67]
	v_mfma_f32_16x16x32_bf16 v[64:67], v[174:177], v[206:209], v[64:67]
	s_barrier
	s_add_i32 s2, s14, s50
	v_lshl_add_u64 v[140:141], v[140:141], 0, s[60:61]
	s_mov_b32 m0, s2
	ds_read_b128 v[178:181], v145 offset:49152
	ds_read_b128 v[182:185], v145 offset:50176
	ds_read_b128 v[186:189], v145 offset:51200
	ds_read_b128 v[190:193], v145 offset:52224
	ds_read_b128 v[194:197], v145 offset:53248
	ds_read_b128 v[198:201], v145 offset:54272
	ds_read_b128 v[202:205], v145 offset:55296
	ds_read_b128 v[206:209], v145 offset:56320
	global_load_lds_dwordx4 v[140:141], off
	s_add_i32 m0, s2, 0x2000
	s_add_u32 s2, s18, 0x30080
	v_lshl_add_u64 v[140:141], v[210:211], 0, s[60:61]
	s_addc_u32 s3, s19, 0
	s_add_i32 s14, s15, s50
	global_load_lds_dwordx4 v[140:141], off
	v_lshl_add_u64 v[140:141], s[2:3], 0, v[132:133]
	s_mov_b32 m0, s14
	s_nop 0
	global_load_lds_dwordx4 v[140:141], off
	v_lshl_add_u64 v[140:141], s[2:3], 0, v[128:129]
	s_add_i32 m0, s14, 0x2000
	s_nop 0
	global_load_lds_dwordx4 v[140:141], off
	v_lshl_add_u64 v[140:141], v[212:213], 0, s[60:61]
	s_mov_b32 m0, s88
	s_nop 0
	global_load_lds_dwordx4 v[140:141], off
	v_lshl_add_u64 v[140:141], v[214:215], 0, s[60:61]
	s_mov_b32 m0, s89
	s_nop 0
	global_load_lds_dwordx4 v[140:141], off
	s_waitcnt vmcnt(8)
	s_waitcnt lgkmcnt(0)
	s_barrier
	v_mfma_f32_16x16x32_bf16 v[60:63], v[146:149], v[178:181], v[60:63]
	v_mfma_f32_16x16x32_bf16 v[60:63], v[150:153], v[182:185], v[60:63]
	v_mfma_f32_16x16x32_bf16 v[44:47], v[146:149], v[186:189], v[44:47]
	v_mfma_f32_16x16x32_bf16 v[44:47], v[150:153], v[190:193], v[44:47]
	v_mfma_f32_16x16x32_bf16 v[28:31], v[146:149], v[194:197], v[28:31]
	v_mfma_f32_16x16x32_bf16 v[28:31], v[150:153], v[198:201], v[28:31]
	v_mfma_f32_16x16x32_bf16 v[12:15], v[146:149], v[202:205], v[12:15]
	v_mfma_f32_16x16x32_bf16 v[12:15], v[150:153], v[206:209], v[12:15]
	v_mfma_f32_16x16x32_bf16 v[56:59], v[154:157], v[178:181], v[56:59]
	v_mfma_f32_16x16x32_bf16 v[56:59], v[158:161], v[182:185], v[56:59]
	v_mfma_f32_16x16x32_bf16 v[40:43], v[154:157], v[186:189], v[40:43]
	v_mfma_f32_16x16x32_bf16 v[40:43], v[158:161], v[190:193], v[40:43]
	v_mfma_f32_16x16x32_bf16 v[24:27], v[154:157], v[194:197], v[24:27]
	v_mfma_f32_16x16x32_bf16 v[24:27], v[158:161], v[198:201], v[24:27]
	v_mfma_f32_16x16x32_bf16 v[8:11], v[154:157], v[202:205], v[8:11]
	v_mfma_f32_16x16x32_bf16 v[8:11], v[158:161], v[206:209], v[8:11]
	v_mfma_f32_16x16x32_bf16 v[52:55], v[162:165], v[178:181], v[52:55]
	v_mfma_f32_16x16x32_bf16 v[52:55], v[166:169], v[182:185], v[52:55]
	v_mfma_f32_16x16x32_bf16 v[36:39], v[162:165], v[186:189], v[36:39]
	v_mfma_f32_16x16x32_bf16 v[36:39], v[166:169], v[190:193], v[36:39]
	v_mfma_f32_16x16x32_bf16 v[20:23], v[162:165], v[194:197], v[20:23]
	v_mfma_f32_16x16x32_bf16 v[20:23], v[166:169], v[198:201], v[20:23]
	v_mfma_f32_16x16x32_bf16 v[4:7], v[162:165], v[202:205], v[4:7]
	v_mfma_f32_16x16x32_bf16 v[4:7], v[166:169], v[206:209], v[4:7]
	v_mfma_f32_16x16x32_bf16 v[48:51], v[170:173], v[178:181], v[48:51]
	v_mfma_f32_16x16x32_bf16 v[48:51], v[174:177], v[182:185], v[48:51]
	v_mfma_f32_16x16x32_bf16 v[32:35], v[170:173], v[186:189], v[32:35]
	v_mfma_f32_16x16x32_bf16 v[32:35], v[174:177], v[190:193], v[32:35]
	v_mfma_f32_16x16x32_bf16 v[16:19], v[170:173], v[194:197], v[16:19]
	v_mfma_f32_16x16x32_bf16 v[16:19], v[174:177], v[198:201], v[16:19]
	v_mfma_f32_16x16x32_bf16 v[0:3], v[170:173], v[202:205], v[0:3]
	v_mfma_f32_16x16x32_bf16 v[0:3], v[174:177], v[206:209], v[0:3]
	s_barrier
	s_add_i32 s95, s95, 2
	s_add_u32 s74, s74, 0x100
	s_addc_u32 s94, s94, 0
	s_cmp_gt_u32 s95, 9
	s_mov_b64 s[14:15], s[16:17]
	s_cbranch_scc0 .LBB0_1326
	s_and_b64 vcc, exec, s[38:39]
	s_cbranch_vccz .LBB0_1329
	s_barrier

.LBB0_1516:
	s_add_u32 s52, s88, 0xfffe0080
	s_addc_u32 s53, s89, -1
	s_add_i32 s58, 0, 0x10000
	s_cmp_eq_u32 vcc_hi, 4
	s_cselect_b32 s55, s17, s53
	s_cselect_b32 s54, s42, s52
	s_cselect_b32 s53, s15, vcc_lo
	s_cselect_b32 s52, s72, s74
	s_add_i32 s81, 0, 0x14000
	v_add_u32_e32 v36, s58, v161
	v_add_u32_e32 v158, s81, v161
	ds_read_b128 v[16:19], v36
	ds_read_b128 v[20:23], v36 offset:1024
	ds_read_b128 v[32:35], v36 offset:2048
	ds_read_b128 v[36:39], v36 offset:3072
	ds_read_b128 v[154:157], v158
	ds_read_b128 v[164:167], v158 offset:1024
	ds_read_b128 v[168:171], v158 offset:2048
	ds_read_b128 v[174:177], v158 offset:3072
	v_lshl_add_u64 v[158:159], s[88:89], 0, v[150:151]
	s_add_i32 m0, s76, 0xc000
	ds_read_b128 v[178:181], v163
	ds_read_b128 v[182:185], v163 offset:1024
	ds_read_b128 v[186:189], v163 offset:2048
	ds_read_b128 v[190:193], v163 offset:3072
	ds_read_b128 v[194:197], v163 offset:4096
	ds_read_b128 v[198:201], v163 offset:5120
	ds_read_b128 v[202:205], v163 offset:6144
	ds_read_b128 v[206:209], v163 offset:7168
	global_load_lds_dwordx4 v[158:159], off
	v_lshl_add_u64 v[158:159], s[88:89], 0, v[152:153]
	s_add_i32 m0, s76, 0xe000
	s_nop 0
	global_load_lds_dwordx4 v[158:159], off
	s_waitcnt vmcnt(8)
	s_waitcnt lgkmcnt(0)
	s_barrier
	v_mfma_f32_16x16x32_bf16 v[140:143], v[16:19], v[178:181], v[140:143]
	v_mfma_f32_16x16x32_bf16 v[140:143], v[20:23], v[182:185], v[140:143]
	v_mfma_f32_16x16x32_bf16 v[124:127], v[16:19], v[186:189], v[124:127]
	v_mfma_f32_16x16x32_bf16 v[124:127], v[20:23], v[190:193], v[124:127]
	v_mfma_f32_16x16x32_bf16 v[108:111], v[16:19], v[194:197], v[108:111]
	v_mfma_f32_16x16x32_bf16 v[108:111], v[20:23], v[198:201], v[108:111]
	v_mfma_f32_16x16x32_bf16 v[92:95], v[16:19], v[202:205], v[92:95]
	v_mfma_f32_16x16x32_bf16 v[92:95], v[20:23], v[206:209], v[92:95]
	v_mfma_f32_16x16x32_bf16 v[136:139], v[32:35], v[178:181], v[136:139]
	v_mfma_f32_16x16x32_bf16 v[136:139], v[36:39], v[182:185], v[136:139]
	v_mfma_f32_16x16x32_bf16 v[120:123], v[32:35], v[186:189], v[120:123]
	v_mfma_f32_16x16x32_bf16 v[120:123], v[36:39], v[190:193], v[120:123]
	v_mfma_f32_16x16x32_bf16 v[104:107], v[32:35], v[194:197], v[104:107]
	v_mfma_f32_16x16x32_bf16 v[104:107], v[36:39], v[198:201], v[104:107]
	v_mfma_f32_16x16x32_bf16 v[88:91], v[32:35], v[202:205], v[88:91]
	v_mfma_f32_16x16x32_bf16 v[88:91], v[36:39], v[206:209], v[88:91]
	v_mfma_f32_16x16x32_bf16 v[132:135], v[154:157], v[178:181], v[132:135]
	v_mfma_f32_16x16x32_bf16 v[132:135], v[164:167], v[182:185], v[132:135]
	v_mfma_f32_16x16x32_bf16 v[116:119], v[154:157], v[186:189], v[116:119]
	v_mfma_f32_16x16x32_bf16 v[116:119], v[164:167], v[190:193], v[116:119]
	v_mfma_f32_16x16x32_bf16 v[100:103], v[154:157], v[194:197], v[100:103]
	v_mfma_f32_16x16x32_bf16 v[100:103], v[164:167], v[198:201], v[100:103]
	v_mfma_f32_16x16x32_bf16 v[84:87], v[154:157], v[202:205], v[84:87]
	v_mfma_f32_16x16x32_bf16 v[84:87], v[164:167], v[206:209], v[84:87]
	v_mfma_f32_16x16x32_bf16 v[128:131], v[168:171], v[178:181], v[128:131]
	v_mfma_f32_16x16x32_bf16 v[128:131], v[174:177], v[182:185], v[128:131]
	v_mfma_f32_16x16x32_bf16 v[112:115], v[168:171], v[186:189], v[112:115]
	v_mfma_f32_16x16x32_bf16 v[112:115], v[174:177], v[190:193], v[112:115]
	v_mfma_f32_16x16x32_bf16 v[96:99], v[168:171], v[194:197], v[96:99]
	v_mfma_f32_16x16x32_bf16 v[96:99], v[174:177], v[198:201], v[96:99]
	v_mfma_f32_16x16x32_bf16 v[80:83], v[168:171], v[202:205], v[80:83]
	v_mfma_f32_16x16x32_bf16 v[80:83], v[174:177], v[206:209], v[80:83]
	s_barrier
	s_add_i32 s58, s58, s50
	v_lshl_add_u64 v[158:159], s[52:53], 0, v[216:217]
	s_mov_b32 m0, s58
	ds_read_b128 v[178:181], v163 offset:16384
	ds_read_b128 v[182:185], v163 offset:17408
	ds_read_b128 v[186:189], v163 offset:18432
	ds_read_b128 v[190:193], v163 offset:19456
	ds_read_b128 v[194:197], v163 offset:20480
	ds_read_b128 v[198:201], v163 offset:21504
	ds_read_b128 v[202:205], v163 offset:22528
	ds_read_b128 v[206:209], v163 offset:23552
	global_load_lds_dwordx4 v[158:159], off
	s_add_i32 m0, s58, 0x2000
	s_add_u32 s58, s52, 0x20000
	v_lshl_add_u64 v[210:211], s[52:53], 0, v[148:149]
	s_addc_u32 s59, s53, 0
	s_add_i32 s81, s81, s50
	global_load_lds_dwordx4 v[210:211], off
	v_lshl_add_u64 v[212:213], s[58:59], 0, v[216:217]
	s_mov_b32 m0, s81
	v_lshl_add_u64 v[214:215], s[54:55], 0, v[146:147]
	global_load_lds_dwordx4 v[212:213], off
	v_lshl_add_u64 v[212:213], s[58:59], 0, v[148:149]
	s_add_i32 m0, s81, 0x2000
	s_nop 0
	global_load_lds_dwordx4 v[212:213], off
	v_lshl_add_u64 v[212:213], s[54:55], 0, v[144:145]
	s_mov_b32 m0, s76
	s_nop 0
	global_load_lds_dwordx4 v[212:213], off
	s_mov_b32 m0, s87
	s_nop 0
	global_load_lds_dwordx4 v[214:215], off
	s_waitcnt vmcnt(8)
	s_waitcnt lgkmcnt(0)
	s_barrier
	v_mfma_f32_16x16x32_bf16 v[76:79], v[16:19], v[178:181], v[76:79]
	v_mfma_f32_16x16x32_bf16 v[76:79], v[20:23], v[182:185], v[76:79]
	v_mfma_f32_16x16x32_bf16 v[60:63], v[16:19], v[186:189], v[60:63]
	v_mfma_f32_16x16x32_bf16 v[60:63], v[20:23], v[190:193], v[60:63]
	v_mfma_f32_16x16x32_bf16 v[44:47], v[16:19], v[194:197], v[44:47]
	v_mfma_f32_16x16x32_bf16 v[44:47], v[20:23], v[198:201], v[44:47]
	v_mfma_f32_16x16x32_bf16 v[12:15], v[16:19], v[202:205], v[12:15]
	v_mfma_f32_16x16x32_bf16 v[12:15], v[20:23], v[206:209], v[12:15]
	v_mfma_f32_16x16x32_bf16 v[72:75], v[32:35], v[178:181], v[72:75]
	v_mfma_f32_16x16x32_bf16 v[72:75], v[36:39], v[182:185], v[72:75]
	v_mfma_f32_16x16x32_bf16 v[56:59], v[32:35], v[186:189], v[56:59]
	v_mfma_f32_16x16x32_bf16 v[56:59], v[36:39], v[190:193], v[56:59]
	v_mfma_f32_16x16x32_bf16 v[40:43], v[32:35], v[194:197], v[40:43]
	v_mfma_f32_16x16x32_bf16 v[40:43], v[36:39], v[198:201], v[40:43]
	v_mfma_f32_16x16x32_bf16 v[8:11], v[32:35], v[202:205], v[8:11]
	v_mfma_f32_16x16x32_bf16 v[8:11], v[36:39], v[206:209], v[8:11]
	v_mfma_f32_16x16x32_bf16 v[28:31], v[154:157], v[194:197], v[28:31]
	v_mfma_f32_16x16x32_bf16 v[24:27], v[168:171], v[194:197], v[24:27]
	v_mfma_f32_16x16x32_bf16 v[0:3], v[154:157], v[202:205], v[0:3]
	v_mfma_f32_16x16x32_bf16 v[4:7], v[168:171], v[202:205], v[4:7]
	v_mfma_f32_16x16x32_bf16 v[16:19], v[154:157], v[178:181], v[68:71]
	v_mfma_f32_16x16x32_bf16 v[20:23], v[168:171], v[178:181], v[64:67]
	v_mfma_f32_16x16x32_bf16 v[32:35], v[154:157], v[186:189], v[52:55]
	v_mfma_f32_16x16x32_bf16 v[36:39], v[168:171], v[186:189], v[48:51]
	v_mfma_f32_16x16x32_bf16 v[28:31], v[164:167], v[198:201], v[28:31]
	v_mfma_f32_16x16x32_bf16 v[24:27], v[174:177], v[198:201], v[24:27]
	v_mfma_f32_16x16x32_bf16 v[0:3], v[164:167], v[206:209], v[0:3]
	v_mfma_f32_16x16x32_bf16 v[4:7], v[174:177], v[206:209], v[4:7]
	v_mfma_f32_16x16x32_bf16 v[16:19], v[164:167], v[182:185], v[16:19]
	v_mfma_f32_16x16x32_bf16 v[20:23], v[174:177], v[182:185], v[20:23]
	v_mfma_f32_16x16x32_bf16 v[32:35], v[164:167], v[190:193], v[32:35]
	v_mfma_f32_16x16x32_bf16 v[36:39], v[174:177], v[190:193], v[36:39]
	s_barrier
	s_add_i32 s58, 0, 0x18000
	s_add_i32 s59, 0, 0x1c000
	v_add_u32_e32 v68, s58, v161
	v_add_u32_e32 v173, s59, v161
	ds_read_b128 v[48:51], v68
	ds_read_b128 v[52:55], v68 offset:1024
	ds_read_b128 v[64:67], v68 offset:2048
	ds_read_b128 v[68:71], v68 offset:3072
	ds_read_b128 v[154:157], v173
	ds_read_b128 v[164:167], v173 offset:1024
	ds_read_b128 v[168:171], v173 offset:2048
	ds_read_b128 v[174:177], v173 offset:3072
	s_add_u32 s54, s54, 0x20000
	s_addc_u32 s55, s55, 0
	s_mov_b32 m0, s25
	v_lshl_add_u64 v[218:219], s[54:55], 0, v[144:145]
	ds_read_b128 v[178:181], v163 offset:32768
	ds_read_b128 v[182:185], v163 offset:33792
	ds_read_b128 v[186:189], v163 offset:34816
	ds_read_b128 v[190:193], v163 offset:35840
	ds_read_b128 v[194:197], v163 offset:36864
	ds_read_b128 v[198:201], v163 offset:37888
	ds_read_b128 v[202:205], v163 offset:38912
	ds_read_b128 v[206:209], v163 offset:39936
	global_load_lds_dwordx4 v[218:219], off
	v_lshl_add_u64 v[218:219], s[54:55], 0, v[146:147]
	s_mov_b32 m0, s65
	s_nop 0
	global_load_lds_dwordx4 v[218:219], off
	s_waitcnt vmcnt(8)
	s_waitcnt lgkmcnt(0)
	s_barrier
	v_mfma_f32_16x16x32_bf16 v[140:143], v[48:51], v[178:181], v[140:143]
	v_mfma_f32_16x16x32_bf16 v[140:143], v[52:55], v[182:185], v[140:143]
	v_mfma_f32_16x16x32_bf16 v[124:127], v[48:51], v[186:189], v[124:127]
	v_mfma_f32_16x16x32_bf16 v[124:127], v[52:55], v[190:193], v[124:127]
	v_mfma_f32_16x16x32_bf16 v[108:111], v[48:51], v[194:197], v[108:111]
	v_mfma_f32_16x16x32_bf16 v[108:111], v[52:55], v[198:201], v[108:111]
	v_mfma_f32_16x16x32_bf16 v[92:95], v[48:51], v[202:205], v[92:95]
	v_mfma_f32_16x16x32_bf16 v[92:95], v[52:55], v[206:209], v[92:95]
	v_mfma_f32_16x16x32_bf16 v[136:139], v[64:67], v[178:181], v[136:139]
	v_mfma_f32_16x16x32_bf16 v[136:139], v[68:71], v[182:185], v[136:139]
	v_mfma_f32_16x16x32_bf16 v[120:123], v[64:67], v[186:189], v[120:123]
	v_mfma_f32_16x16x32_bf16 v[120:123], v[68:71], v[190:193], v[120:123]
	v_mfma_f32_16x16x32_bf16 v[104:107], v[64:67], v[194:197], v[104:107]
	v_mfma_f32_16x16x32_bf16 v[104:107], v[68:71], v[198:201], v[104:107]
	v_mfma_f32_16x16x32_bf16 v[88:91], v[64:67], v[202:205], v[88:91]
	v_mfma_f32_16x16x32_bf16 v[88:91], v[68:71], v[206:209], v[88:91]
	v_mfma_f32_16x16x32_bf16 v[132:135], v[154:157], v[178:181], v[132:135]
	v_mfma_f32_16x16x32_bf16 v[132:135], v[164:167], v[182:185], v[132:135]
	v_mfma_f32_16x16x32_bf16 v[116:119], v[154:157], v[186:189], v[116:119]
	v_mfma_f32_16x16x32_bf16 v[116:119], v[164:167], v[190:193], v[116:119]
	v_mfma_f32_16x16x32_bf16 v[100:103], v[154:157], v[194:197], v[100:103]
	v_mfma_f32_16x16x32_bf16 v[100:103], v[164:167], v[198:201], v[100:103]
	v_mfma_f32_16x16x32_bf16 v[84:87], v[154:157], v[202:205], v[84:87]
	v_mfma_f32_16x16x32_bf16 v[84:87], v[164:167], v[206:209], v[84:87]
	v_mfma_f32_16x16x32_bf16 v[128:131], v[168:171], v[178:181], v[128:131]
	v_mfma_f32_16x16x32_bf16 v[128:131], v[174:177], v[182:185], v[128:131]
	v_mfma_f32_16x16x32_bf16 v[112:115], v[168:171], v[186:189], v[112:115]
	v_mfma_f32_16x16x32_bf16 v[112:115], v[174:177], v[190:193], v[112:115]
	v_mfma_f32_16x16x32_bf16 v[96:99], v[168:171], v[194:197], v[96:99]
	v_mfma_f32_16x16x32_bf16 v[96:99], v[174:177], v[198:201], v[96:99]
	v_mfma_f32_16x16x32_bf16 v[80:83], v[168:171], v[202:205], v[80:83]
	v_mfma_f32_16x16x32_bf16 v[80:83], v[174:177], v[206:209], v[80:83]
	s_barrier
	s_add_i32 s54, s58, s50
	v_lshl_add_u64 v[158:159], v[158:159], 0, s[60:61]
	s_mov_b32 m0, s54
	ds_read_b128 v[178:181], v163 offset:49152
	ds_read_b128 v[182:185], v163 offset:50176
	ds_read_b128 v[186:189], v163 offset:51200
	ds_read_b128 v[190:193], v163 offset:52224
	ds_read_b128 v[194:197], v163 offset:53248
	ds_read_b128 v[198:201], v163 offset:54272
	ds_read_b128 v[202:205], v163 offset:55296
	ds_read_b128 v[206:209], v163 offset:56320
	global_load_lds_dwordx4 v[158:159], off
	s_add_i32 m0, s54, 0x2000
	s_add_u32 s52, s52, 0x20080
	v_lshl_add_u64 v[158:159], v[210:211], 0, s[60:61]
	s_addc_u32 s53, s53, 0
	s_add_i32 s54, s59, s50
	global_load_lds_dwordx4 v[158:159], off
	v_lshl_add_u64 v[158:159], s[52:53], 0, v[216:217]
	s_mov_b32 m0, s54
	s_nop 0
	global_load_lds_dwordx4 v[158:159], off
	v_lshl_add_u64 v[158:159], s[52:53], 0, v[148:149]
	s_add_i32 m0, s54, 0x2000
	s_nop 0
	global_load_lds_dwordx4 v[158:159], off
	v_lshl_add_u64 v[158:159], v[212:213], 0, s[60:61]
	s_mov_b32 m0, s85
	s_nop 0
	global_load_lds_dwordx4 v[158:159], off
	v_lshl_add_u64 v[158:159], v[214:215], 0, s[60:61]
	s_mov_b32 m0, s21
	s_nop 0
	global_load_lds_dwordx4 v[158:159], off
	s_waitcnt vmcnt(8)
	s_waitcnt lgkmcnt(0)
	s_barrier
	v_mfma_f32_16x16x32_bf16 v[76:79], v[48:51], v[178:181], v[76:79]
	v_mfma_f32_16x16x32_bf16 v[76:79], v[52:55], v[182:185], v[76:79]
	v_mfma_f32_16x16x32_bf16 v[60:63], v[48:51], v[186:189], v[60:63]
	v_mfma_f32_16x16x32_bf16 v[60:63], v[52:55], v[190:193], v[60:63]
	v_mfma_f32_16x16x32_bf16 v[44:47], v[48:51], v[194:197], v[44:47]
	v_mfma_f32_16x16x32_bf16 v[44:47], v[52:55], v[198:201], v[44:47]
	v_mfma_f32_16x16x32_bf16 v[12:15], v[48:51], v[202:205], v[12:15]
	v_mfma_f32_16x16x32_bf16 v[12:15], v[52:55], v[206:209], v[12:15]
	v_mfma_f32_16x16x32_bf16 v[72:75], v[64:67], v[178:181], v[72:75]
	v_mfma_f32_16x16x32_bf16 v[72:75], v[68:71], v[182:185], v[72:75]
	v_mfma_f32_16x16x32_bf16 v[56:59], v[64:67], v[186:189], v[56:59]
	v_mfma_f32_16x16x32_bf16 v[56:59], v[68:71], v[190:193], v[56:59]
	v_mfma_f32_16x16x32_bf16 v[40:43], v[64:67], v[194:197], v[40:43]
	v_mfma_f32_16x16x32_bf16 v[40:43], v[68:71], v[198:201], v[40:43]
	v_mfma_f32_16x16x32_bf16 v[8:11], v[64:67], v[202:205], v[8:11]
	v_mfma_f32_16x16x32_bf16 v[8:11], v[68:71], v[206:209], v[8:11]
	v_mfma_f32_16x16x32_bf16 v[16:19], v[154:157], v[178:181], v[16:19]
	v_mfma_f32_16x16x32_bf16 v[68:71], v[164:167], v[182:185], v[16:19]
	v_mfma_f32_16x16x32_bf16 v[16:19], v[168:171], v[178:181], v[20:23]
	v_mfma_f32_16x16x32_bf16 v[64:67], v[174:177], v[182:185], v[16:19]
	v_mfma_f32_16x16x32_bf16 v[16:19], v[154:157], v[186:189], v[32:35]
	v_mfma_f32_16x16x32_bf16 v[52:55], v[164:167], v[190:193], v[16:19]
	v_mfma_f32_16x16x32_bf16 v[16:19], v[168:171], v[186:189], v[36:39]
	v_mfma_f32_16x16x32_bf16 v[48:51], v[174:177], v[190:193], v[16:19]
	v_mfma_f32_16x16x32_bf16 v[16:19], v[154:157], v[194:197], v[28:31]
	v_mfma_f32_16x16x32_bf16 v[28:31], v[164:167], v[198:201], v[16:19]
	v_mfma_f32_16x16x32_bf16 v[16:19], v[168:171], v[194:197], v[24:27]
	v_mfma_f32_16x16x32_bf16 v[0:3], v[154:157], v[202:205], v[0:3]
	v_mfma_f32_16x16x32_bf16 v[4:7], v[168:171], v[202:205], v[4:7]
	v_mfma_f32_16x16x32_bf16 v[24:27], v[174:177], v[198:201], v[16:19]
	v_mfma_f32_16x16x32_bf16 v[0:3], v[164:167], v[206:209], v[0:3]
	v_mfma_f32_16x16x32_bf16 v[4:7], v[174:177], v[206:209], v[4:7]
	s_barrier
	s_add_i32 vcc_hi, vcc_hi, 2
	s_add_u32 s88, s88, 0x100
	s_addc_u32 s89, s89, 0
	s_add_u32 s74, s74, 0x100
	s_addc_u32 vcc_lo, vcc_lo, 0
	s_cmp_gt_u32 vcc_hi, 5
	s_cbranch_scc0 .LBB0_1516
	s_and_b64 vcc, exec, s[38:39]
	s_cbranch_vccz .LBB0_1519
	s_barrier

.LBB0_1664:
	s_add_u32 s52, s90, 0xfff80080
	s_addc_u32 s53, s91, -1
	s_add_i32 s58, 0, 0x10000
	s_cmp_eq_u32 vcc_lo, 28
	s_cselect_b32 s55, s17, s53
	s_cselect_b32 s54, s96, s52
	s_cselect_b32 s53, s15, s93
	s_cselect_b32 s52, s97, s92
	s_add_i32 s81, 0, 0x14000
	v_add_u32_e32 v140, s58, v163
	v_add_u32_e32 v170, s81, v163
	ds_read_b128 v[128:131], v140
	ds_read_b128 v[132:135], v140 offset:1024
	ds_read_b128 v[136:139], v140 offset:2048
	ds_read_b128 v[140:143], v140 offset:3072
	ds_read_b128 v[154:157], v170
	ds_read_b128 v[158:161], v170 offset:1024
	ds_read_b128 v[166:169], v170 offset:2048
	ds_read_b128 v[174:177], v170 offset:3072
	v_lshl_add_u64 v[170:171], s[90:91], 0, v[150:151]
	s_add_i32 m0, s76, 0xc000
	ds_read_b128 v[178:181], v165
	ds_read_b128 v[182:185], v165 offset:1024
	ds_read_b128 v[186:189], v165 offset:2048
	ds_read_b128 v[190:193], v165 offset:3072
	ds_read_b128 v[194:197], v165 offset:4096
	ds_read_b128 v[198:201], v165 offset:5120
	ds_read_b128 v[202:205], v165 offset:6144
	ds_read_b128 v[206:209], v165 offset:7168
	global_load_lds_dwordx4 v[170:171], off
	v_lshl_add_u64 v[170:171], s[90:91], 0, v[152:153]
	s_add_i32 m0, s76, 0xe000
	s_nop 0
	global_load_lds_dwordx4 v[170:171], off
	s_waitcnt vmcnt(8)
	s_waitcnt lgkmcnt(0)
	s_barrier
	v_mfma_f32_16x16x32_bf16 v[124:127], v[128:131], v[178:181], v[124:127]
	v_mfma_f32_16x16x32_bf16 v[124:127], v[132:135], v[182:185], v[124:127]
	v_mfma_f32_16x16x32_bf16 v[116:119], v[128:131], v[186:189], v[116:119]
	v_mfma_f32_16x16x32_bf16 v[116:119], v[132:135], v[190:193], v[116:119]
	v_mfma_f32_16x16x32_bf16 v[96:99], v[128:131], v[194:197], v[96:99]
	v_mfma_f32_16x16x32_bf16 v[96:99], v[132:135], v[198:201], v[96:99]
	v_mfma_f32_16x16x32_bf16 v[80:83], v[128:131], v[202:205], v[80:83]
	v_mfma_f32_16x16x32_bf16 v[80:83], v[132:135], v[206:209], v[80:83]
	v_mfma_f32_16x16x32_bf16 v[120:123], v[136:139], v[178:181], v[120:123]
	v_mfma_f32_16x16x32_bf16 v[120:123], v[140:143], v[182:185], v[120:123]
	v_mfma_f32_16x16x32_bf16 v[112:115], v[136:139], v[186:189], v[112:115]
	v_mfma_f32_16x16x32_bf16 v[112:115], v[140:143], v[190:193], v[112:115]
	v_mfma_f32_16x16x32_bf16 v[88:91], v[136:139], v[194:197], v[88:91]
	v_mfma_f32_16x16x32_bf16 v[88:91], v[140:143], v[198:201], v[88:91]
	v_mfma_f32_16x16x32_bf16 v[72:75], v[136:139], v[202:205], v[72:75]
	v_mfma_f32_16x16x32_bf16 v[72:75], v[140:143], v[206:209], v[72:75]
	v_mfma_f32_16x16x32_bf16 v[108:111], v[154:157], v[178:181], v[108:111]
	v_mfma_f32_16x16x32_bf16 v[108:111], v[158:161], v[182:185], v[108:111]
	v_mfma_f32_16x16x32_bf16 v[100:103], v[154:157], v[186:189], v[100:103]
	v_mfma_f32_16x16x32_bf16 v[100:103], v[158:161], v[190:193], v[100:103]
	v_mfma_f32_16x16x32_bf16 v[84:87], v[154:157], v[194:197], v[84:87]
	v_mfma_f32_16x16x32_bf16 v[84:87], v[158:161], v[198:201], v[84:87]
	v_mfma_f32_16x16x32_bf16 v[68:71], v[154:157], v[202:205], v[68:71]
	v_mfma_f32_16x16x32_bf16 v[68:71], v[158:161], v[206:209], v[68:71]
	v_mfma_f32_16x16x32_bf16 v[104:107], v[166:169], v[178:181], v[104:107]
	v_mfma_f32_16x16x32_bf16 v[104:107], v[174:177], v[182:185], v[104:107]
	v_mfma_f32_16x16x32_bf16 v[92:95], v[166:169], v[186:189], v[92:95]
	v_mfma_f32_16x16x32_bf16 v[92:95], v[174:177], v[190:193], v[92:95]
	v_mfma_f32_16x16x32_bf16 v[76:79], v[166:169], v[194:197], v[76:79]
	v_mfma_f32_16x16x32_bf16 v[76:79], v[174:177], v[198:201], v[76:79]
	v_mfma_f32_16x16x32_bf16 v[64:67], v[166:169], v[202:205], v[64:67]
	v_mfma_f32_16x16x32_bf16 v[64:67], v[174:177], v[206:209], v[64:67]
	s_barrier
	s_add_i32 s58, s58, s50
	v_lshl_add_u64 v[170:171], s[52:53], 0, v[216:217]
	s_mov_b32 m0, s58
	ds_read_b128 v[178:181], v165 offset:16384
	ds_read_b128 v[182:185], v165 offset:17408
	ds_read_b128 v[186:189], v165 offset:18432
	ds_read_b128 v[190:193], v165 offset:19456
	ds_read_b128 v[194:197], v165 offset:20480
	ds_read_b128 v[198:201], v165 offset:21504
	ds_read_b128 v[202:205], v165 offset:22528
	ds_read_b128 v[206:209], v165 offset:23552
	global_load_lds_dwordx4 v[170:171], off
	s_add_i32 m0, s58, 0x2000
	s_add_u32 s58, s52, 0x80000
	v_lshl_add_u64 v[210:211], s[52:53], 0, v[148:149]
	s_addc_u32 s59, s53, 0
	s_add_i32 s81, s81, s50
	global_load_lds_dwordx4 v[210:211], off
	v_lshl_add_u64 v[212:213], s[58:59], 0, v[216:217]
	s_mov_b32 m0, s81
	v_lshl_add_u64 v[214:215], s[54:55], 0, v[146:147]
	global_load_lds_dwordx4 v[212:213], off
	v_lshl_add_u64 v[212:213], s[58:59], 0, v[148:149]
	s_add_i32 m0, s81, 0x2000
	s_nop 0
	global_load_lds_dwordx4 v[212:213], off
	v_lshl_add_u64 v[212:213], s[54:55], 0, v[144:145]
	s_mov_b32 m0, s76
	s_nop 0
	global_load_lds_dwordx4 v[212:213], off
	s_mov_b32 m0, s45
	s_nop 0
	global_load_lds_dwordx4 v[214:215], off
	s_waitcnt vmcnt(8)
	s_waitcnt lgkmcnt(0)
	s_barrier
	v_mfma_f32_16x16x32_bf16 v[60:63], v[128:131], v[178:181], v[60:63]
	v_mfma_f32_16x16x32_bf16 v[60:63], v[132:135], v[182:185], v[60:63]
	v_mfma_f32_16x16x32_bf16 v[48:51], v[128:131], v[186:189], v[48:51]
	v_mfma_f32_16x16x32_bf16 v[48:51], v[132:135], v[190:193], v[48:51]
	v_mfma_f32_16x16x32_bf16 v[32:35], v[128:131], v[194:197], v[32:35]
	v_mfma_f32_16x16x32_bf16 v[32:35], v[132:135], v[198:201], v[32:35]
	v_mfma_f32_16x16x32_bf16 v[16:19], v[128:131], v[202:205], v[16:19]
	v_mfma_f32_16x16x32_bf16 v[16:19], v[132:135], v[206:209], v[16:19]
	v_mfma_f32_16x16x32_bf16 v[56:59], v[136:139], v[178:181], v[56:59]
	v_mfma_f32_16x16x32_bf16 v[56:59], v[140:143], v[182:185], v[56:59]
	v_mfma_f32_16x16x32_bf16 v[40:43], v[136:139], v[186:189], v[40:43]
	v_mfma_f32_16x16x32_bf16 v[40:43], v[140:143], v[190:193], v[40:43]
	v_mfma_f32_16x16x32_bf16 v[24:27], v[136:139], v[194:197], v[24:27]
	v_mfma_f32_16x16x32_bf16 v[24:27], v[140:143], v[198:201], v[24:27]
	v_mfma_f32_16x16x32_bf16 v[8:11], v[136:139], v[202:205], v[8:11]
	v_mfma_f32_16x16x32_bf16 v[8:11], v[140:143], v[206:209], v[8:11]
	v_mfma_f32_16x16x32_bf16 v[52:55], v[154:157], v[178:181], v[52:55]
	v_mfma_f32_16x16x32_bf16 v[52:55], v[158:161], v[182:185], v[52:55]
	v_mfma_f32_16x16x32_bf16 v[36:39], v[154:157], v[186:189], v[36:39]
	v_mfma_f32_16x16x32_bf16 v[36:39], v[158:161], v[190:193], v[36:39]
	v_mfma_f32_16x16x32_bf16 v[20:23], v[154:157], v[194:197], v[20:23]
	v_mfma_f32_16x16x32_bf16 v[20:23], v[158:161], v[198:201], v[20:23]
	v_mfma_f32_16x16x32_bf16 v[4:7], v[154:157], v[202:205], v[4:7]
	v_mfma_f32_16x16x32_bf16 v[4:7], v[158:161], v[206:209], v[4:7]
	v_mfma_f32_16x16x32_bf16 v[44:47], v[166:169], v[178:181], v[44:47]
	v_mfma_f32_16x16x32_bf16 v[44:47], v[174:177], v[182:185], v[44:47]
	v_mfma_f32_16x16x32_bf16 v[28:31], v[166:169], v[186:189], v[28:31]
	v_mfma_f32_16x16x32_bf16 v[28:31], v[174:177], v[190:193], v[28:31]
	v_mfma_f32_16x16x32_bf16 v[12:15], v[166:169], v[194:197], v[12:15]
	v_mfma_f32_16x16x32_bf16 v[12:15], v[174:177], v[198:201], v[12:15]
	v_mfma_f32_16x16x32_bf16 v[0:3], v[166:169], v[202:205], v[0:3]
	v_mfma_f32_16x16x32_bf16 v[0:3], v[174:177], v[206:209], v[0:3]
	s_barrier
	s_add_i32 s58, 0, 0x18000
	s_add_i32 s59, 0, 0x1c000
	v_add_u32_e32 v140, s58, v163
	v_add_u32_e32 v173, s59, v163
	ds_read_b128 v[128:131], v140
	ds_read_b128 v[132:135], v140 offset:1024
	ds_read_b128 v[136:139], v140 offset:2048
	ds_read_b128 v[140:143], v140 offset:3072
	ds_read_b128 v[154:157], v173
	ds_read_b128 v[158:161], v173 offset:1024
	ds_read_b128 v[166:169], v173 offset:2048
	ds_read_b128 v[174:177], v173 offset:3072
	s_add_u32 s54, s54, 0x80000
	s_addc_u32 s55, s55, 0
	s_mov_b32 m0, s65
	v_lshl_add_u64 v[218:219], s[54:55], 0, v[144:145]
	ds_read_b128 v[178:181], v165 offset:32768
	ds_read_b128 v[182:185], v165 offset:33792
	ds_read_b128 v[186:189], v165 offset:34816
	ds_read_b128 v[190:193], v165 offset:35840
	ds_read_b128 v[194:197], v165 offset:36864
	ds_read_b128 v[198:201], v165 offset:37888
	ds_read_b128 v[202:205], v165 offset:38912
	ds_read_b128 v[206:209], v165 offset:39936
	global_load_lds_dwordx4 v[218:219], off
	v_lshl_add_u64 v[218:219], s[54:55], 0, v[146:147]
	s_mov_b32 m0, s72
	s_nop 0
	global_load_lds_dwordx4 v[218:219], off
	s_waitcnt vmcnt(8)
	s_waitcnt lgkmcnt(0)
	s_barrier
	v_mfma_f32_16x16x32_bf16 v[124:127], v[128:131], v[178:181], v[124:127]
	v_mfma_f32_16x16x32_bf16 v[124:127], v[132:135], v[182:185], v[124:127]
	v_mfma_f32_16x16x32_bf16 v[116:119], v[128:131], v[186:189], v[116:119]
	v_mfma_f32_16x16x32_bf16 v[116:119], v[132:135], v[190:193], v[116:119]
	v_mfma_f32_16x16x32_bf16 v[96:99], v[128:131], v[194:197], v[96:99]
	v_mfma_f32_16x16x32_bf16 v[96:99], v[132:135], v[198:201], v[96:99]
	v_mfma_f32_16x16x32_bf16 v[80:83], v[128:131], v[202:205], v[80:83]
	v_mfma_f32_16x16x32_bf16 v[80:83], v[132:135], v[206:209], v[80:83]
	v_mfma_f32_16x16x32_bf16 v[120:123], v[136:139], v[178:181], v[120:123]
	v_mfma_f32_16x16x32_bf16 v[120:123], v[140:143], v[182:185], v[120:123]
	v_mfma_f32_16x16x32_bf16 v[112:115], v[136:139], v[186:189], v[112:115]
	v_mfma_f32_16x16x32_bf16 v[112:115], v[140:143], v[190:193], v[112:115]
	v_mfma_f32_16x16x32_bf16 v[88:91], v[136:139], v[194:197], v[88:91]
	v_mfma_f32_16x16x32_bf16 v[88:91], v[140:143], v[198:201], v[88:91]
	v_mfma_f32_16x16x32_bf16 v[72:75], v[136:139], v[202:205], v[72:75]
	v_mfma_f32_16x16x32_bf16 v[72:75], v[140:143], v[206:209], v[72:75]
	v_mfma_f32_16x16x32_bf16 v[108:111], v[154:157], v[178:181], v[108:111]
	v_mfma_f32_16x16x32_bf16 v[108:111], v[158:161], v[182:185], v[108:111]
	v_mfma_f32_16x16x32_bf16 v[100:103], v[154:157], v[186:189], v[100:103]
	v_mfma_f32_16x16x32_bf16 v[100:103], v[158:161], v[190:193], v[100:103]
	v_mfma_f32_16x16x32_bf16 v[84:87], v[154:157], v[194:197], v[84:87]
	v_mfma_f32_16x16x32_bf16 v[84:87], v[158:161], v[198:201], v[84:87]
	v_mfma_f32_16x16x32_bf16 v[68:71], v[154:157], v[202:205], v[68:71]
	v_mfma_f32_16x16x32_bf16 v[68:71], v[158:161], v[206:209], v[68:71]
	v_mfma_f32_16x16x32_bf16 v[104:107], v[166:169], v[178:181], v[104:107]
	v_mfma_f32_16x16x32_bf16 v[104:107], v[174:177], v[182:185], v[104:107]
	v_mfma_f32_16x16x32_bf16 v[92:95], v[166:169], v[186:189], v[92:95]
	v_mfma_f32_16x16x32_bf16 v[92:95], v[174:177], v[190:193], v[92:95]
	v_mfma_f32_16x16x32_bf16 v[76:79], v[166:169], v[194:197], v[76:79]
	v_mfma_f32_16x16x32_bf16 v[76:79], v[174:177], v[198:201], v[76:79]
	v_mfma_f32_16x16x32_bf16 v[64:67], v[166:169], v[202:205], v[64:67]
	v_mfma_f32_16x16x32_bf16 v[64:67], v[174:177], v[206:209], v[64:67]
	s_barrier
	s_add_i32 s54, s58, s50
	v_lshl_add_u64 v[170:171], v[170:171], 0, s[60:61]
	s_mov_b32 m0, s54
	ds_read_b128 v[178:181], v165 offset:49152
	ds_read_b128 v[182:185], v165 offset:50176
	ds_read_b128 v[186:189], v165 offset:51200
	ds_read_b128 v[190:193], v165 offset:52224
	ds_read_b128 v[194:197], v165 offset:53248
	ds_read_b128 v[198:201], v165 offset:54272
	ds_read_b128 v[202:205], v165 offset:55296
	ds_read_b128 v[206:209], v165 offset:56320
	global_load_lds_dwordx4 v[170:171], off
	s_add_i32 m0, s54, 0x2000
	s_add_u32 s52, s52, 0x80080
	v_lshl_add_u64 v[170:171], v[210:211], 0, s[60:61]
	s_addc_u32 s53, s53, 0
	s_add_i32 s54, s59, s50
	global_load_lds_dwordx4 v[170:171], off
	v_lshl_add_u64 v[170:171], s[52:53], 0, v[216:217]
	s_mov_b32 m0, s54
	s_nop 0
	global_load_lds_dwordx4 v[170:171], off
	v_lshl_add_u64 v[170:171], s[52:53], 0, v[148:149]
	s_add_i32 m0, s54, 0x2000
	s_nop 0
	global_load_lds_dwordx4 v[170:171], off
	v_lshl_add_u64 v[170:171], v[212:213], 0, s[60:61]
	s_mov_b32 m0, s87
	s_nop 0
	global_load_lds_dwordx4 v[170:171], off
	v_lshl_add_u64 v[170:171], v[214:215], 0, s[60:61]
	s_mov_b32 m0, s89
	s_nop 0
	global_load_lds_dwordx4 v[170:171], off
	s_waitcnt vmcnt(8)
	s_waitcnt lgkmcnt(0)
	s_barrier
	v_mfma_f32_16x16x32_bf16 v[60:63], v[128:131], v[178:181], v[60:63]
	v_mfma_f32_16x16x32_bf16 v[60:63], v[132:135], v[182:185], v[60:63]
	v_mfma_f32_16x16x32_bf16 v[48:51], v[128:131], v[186:189], v[48:51]
	v_mfma_f32_16x16x32_bf16 v[48:51], v[132:135], v[190:193], v[48:51]
	v_mfma_f32_16x16x32_bf16 v[32:35], v[128:131], v[194:197], v[32:35]
	v_mfma_f32_16x16x32_bf16 v[32:35], v[132:135], v[198:201], v[32:35]
	v_mfma_f32_16x16x32_bf16 v[16:19], v[128:131], v[202:205], v[16:19]
	v_mfma_f32_16x16x32_bf16 v[16:19], v[132:135], v[206:209], v[16:19]
	v_mfma_f32_16x16x32_bf16 v[56:59], v[136:139], v[178:181], v[56:59]
	v_mfma_f32_16x16x32_bf16 v[56:59], v[140:143], v[182:185], v[56:59]
	v_mfma_f32_16x16x32_bf16 v[40:43], v[136:139], v[186:189], v[40:43]
	v_mfma_f32_16x16x32_bf16 v[40:43], v[140:143], v[190:193], v[40:43]
	v_mfma_f32_16x16x32_bf16 v[24:27], v[136:139], v[194:197], v[24:27]
	v_mfma_f32_16x16x32_bf16 v[24:27], v[140:143], v[198:201], v[24:27]
	v_mfma_f32_16x16x32_bf16 v[8:11], v[136:139], v[202:205], v[8:11]
	v_mfma_f32_16x16x32_bf16 v[8:11], v[140:143], v[206:209], v[8:11]
	v_mfma_f32_16x16x32_bf16 v[52:55], v[154:157], v[178:181], v[52:55]
	v_mfma_f32_16x16x32_bf16 v[52:55], v[158:161], v[182:185], v[52:55]
	v_mfma_f32_16x16x32_bf16 v[36:39], v[154:157], v[186:189], v[36:39]
	v_mfma_f32_16x16x32_bf16 v[36:39], v[158:161], v[190:193], v[36:39]
	v_mfma_f32_16x16x32_bf16 v[20:23], v[154:157], v[194:197], v[20:23]
	v_mfma_f32_16x16x32_bf16 v[20:23], v[158:161], v[198:201], v[20:23]
	v_mfma_f32_16x16x32_bf16 v[4:7], v[154:157], v[202:205], v[4:7]
	v_mfma_f32_16x16x32_bf16 v[4:7], v[158:161], v[206:209], v[4:7]
	v_mfma_f32_16x16x32_bf16 v[44:47], v[166:169], v[178:181], v[44:47]
	v_mfma_f32_16x16x32_bf16 v[44:47], v[174:177], v[182:185], v[44:47]
	v_mfma_f32_16x16x32_bf16 v[28:31], v[166:169], v[186:189], v[28:31]
	v_mfma_f32_16x16x32_bf16 v[28:31], v[174:177], v[190:193], v[28:31]
	v_mfma_f32_16x16x32_bf16 v[12:15], v[166:169], v[194:197], v[12:15]
	v_mfma_f32_16x16x32_bf16 v[12:15], v[174:177], v[198:201], v[12:15]
	v_mfma_f32_16x16x32_bf16 v[0:3], v[166:169], v[202:205], v[0:3]
	v_mfma_f32_16x16x32_bf16 v[0:3], v[174:177], v[206:209], v[0:3]
	s_barrier
	s_add_i32 vcc_lo, vcc_lo, 2
	s_add_u32 s90, s90, 0x100
	s_addc_u32 s91, s91, 0
	s_add_u32 s92, s92, 0x100
	s_addc_u32 s93, s93, 0
	s_cmp_gt_u32 vcc_lo, 29
	s_cbranch_scc0 .LBB0_1664
	s_and_b64 vcc, exec, s[38:39]
	s_cbranch_vccz .LBB0_1667
	s_barrier

.LBB0_1931:
	s_add_u32 s52, s22, 0xfff80080
	s_addc_u32 s53, s23, -1
	s_add_i32 s58, 0, 0x10000
	s_cmp_eq_u32 s95, 28
	s_cselect_b32 s55, s13, s53
	s_cselect_b32 s54, s91, s52
	v_add_u32_e32 v138, s58, v141
	s_cselect_b32 s53, s11, s94
	s_cselect_b32 s52, s92, s93
	s_add_i32 s81, 0, 0x14000
	ds_read_b128 v[144:147], v138
	ds_read_b128 v[148:151], v138 offset:1024
	ds_read_b128 v[152:155], v138 offset:2048
	ds_read_b128 v[156:159], v138 offset:3072
	v_add_u32_e32 v138, s81, v141
	ds_read_b128 v[160:163], v138
	ds_read_b128 v[164:167], v138 offset:1024
	ds_read_b128 v[168:171], v138 offset:2048
	ds_read_b128 v[174:177], v138 offset:3072
	v_lshl_add_u64 v[138:139], s[22:23], 0, v[134:135]
	s_add_i32 m0, s76, 0xc000
	ds_read_b128 v[178:181], v143
	ds_read_b128 v[182:185], v143 offset:1024
	ds_read_b128 v[186:189], v143 offset:2048
	ds_read_b128 v[190:193], v143 offset:3072
	ds_read_b128 v[194:197], v143 offset:4096
	ds_read_b128 v[198:201], v143 offset:5120
	ds_read_b128 v[202:205], v143 offset:6144
	ds_read_b128 v[206:209], v143 offset:7168
	global_load_lds_dwordx4 v[138:139], off
	v_lshl_add_u64 v[138:139], s[22:23], 0, v[136:137]
	s_add_i32 m0, s76, 0xe000
	s_nop 0
	global_load_lds_dwordx4 v[138:139], off
	s_waitcnt vmcnt(8)
	s_waitcnt lgkmcnt(0)
	s_barrier
	v_mfma_f32_16x16x32_bf16 v[120:123], v[144:147], v[178:181], v[120:123]
	v_mfma_f32_16x16x32_bf16 v[120:123], v[148:151], v[182:185], v[120:123]
	v_mfma_f32_16x16x32_bf16 v[104:107], v[144:147], v[186:189], v[104:107]
	v_mfma_f32_16x16x32_bf16 v[104:107], v[148:151], v[190:193], v[104:107]
	v_mfma_f32_16x16x32_bf16 v[88:91], v[144:147], v[194:197], v[88:91]
	v_mfma_f32_16x16x32_bf16 v[88:91], v[148:151], v[198:201], v[88:91]
	v_mfma_f32_16x16x32_bf16 v[72:75], v[144:147], v[202:205], v[72:75]
	v_mfma_f32_16x16x32_bf16 v[72:75], v[148:151], v[206:209], v[72:75]
	v_mfma_f32_16x16x32_bf16 v[112:115], v[152:155], v[178:181], v[112:115]
	v_mfma_f32_16x16x32_bf16 v[112:115], v[156:159], v[182:185], v[112:115]
	v_mfma_f32_16x16x32_bf16 v[96:99], v[152:155], v[186:189], v[96:99]
	v_mfma_f32_16x16x32_bf16 v[96:99], v[156:159], v[190:193], v[96:99]
	v_mfma_f32_16x16x32_bf16 v[80:83], v[152:155], v[194:197], v[80:83]
	v_mfma_f32_16x16x32_bf16 v[80:83], v[156:159], v[198:201], v[80:83]
	v_mfma_f32_16x16x32_bf16 v[64:67], v[152:155], v[202:205], v[64:67]
	v_mfma_f32_16x16x32_bf16 v[64:67], v[156:159], v[206:209], v[64:67]
	v_mfma_f32_16x16x32_bf16 v[124:127], v[160:163], v[178:181], v[124:127]
	v_mfma_f32_16x16x32_bf16 v[124:127], v[164:167], v[182:185], v[124:127]
	v_mfma_f32_16x16x32_bf16 v[108:111], v[160:163], v[186:189], v[108:111]
	v_mfma_f32_16x16x32_bf16 v[108:111], v[164:167], v[190:193], v[108:111]
	v_mfma_f32_16x16x32_bf16 v[92:95], v[160:163], v[194:197], v[92:95]
	v_mfma_f32_16x16x32_bf16 v[92:95], v[164:167], v[198:201], v[92:95]
	v_mfma_f32_16x16x32_bf16 v[76:79], v[160:163], v[202:205], v[76:79]
	v_mfma_f32_16x16x32_bf16 v[76:79], v[164:167], v[206:209], v[76:79]
	v_mfma_f32_16x16x32_bf16 v[116:119], v[168:171], v[178:181], v[116:119]
	v_mfma_f32_16x16x32_bf16 v[116:119], v[174:177], v[182:185], v[116:119]
	v_mfma_f32_16x16x32_bf16 v[100:103], v[168:171], v[186:189], v[100:103]
	v_mfma_f32_16x16x32_bf16 v[100:103], v[174:177], v[190:193], v[100:103]
	v_mfma_f32_16x16x32_bf16 v[84:87], v[168:171], v[194:197], v[84:87]
	v_mfma_f32_16x16x32_bf16 v[84:87], v[174:177], v[198:201], v[84:87]
	v_mfma_f32_16x16x32_bf16 v[68:71], v[168:171], v[202:205], v[68:71]
	v_mfma_f32_16x16x32_bf16 v[68:71], v[174:177], v[206:209], v[68:71]
	s_barrier
	s_add_i32 s58, s58, s50
	v_lshl_add_u64 v[138:139], s[52:53], 0, v[216:217]
	s_mov_b32 m0, s58
	ds_read_b128 v[178:181], v143 offset:16384
	ds_read_b128 v[182:185], v143 offset:17408
	ds_read_b128 v[186:189], v143 offset:18432
	ds_read_b128 v[190:193], v143 offset:19456
	ds_read_b128 v[194:197], v143 offset:20480
	ds_read_b128 v[198:201], v143 offset:21504
	ds_read_b128 v[202:205], v143 offset:22528
	ds_read_b128 v[206:209], v143 offset:23552
	global_load_lds_dwordx4 v[138:139], off
	s_add_i32 m0, s58, 0x2000
	s_add_u32 s58, s52, 0x80000
	v_lshl_add_u64 v[210:211], s[52:53], 0, v[132:133]
	s_addc_u32 s59, s53, 0
	s_add_i32 s81, s81, s50
	global_load_lds_dwordx4 v[210:211], off
	v_lshl_add_u64 v[212:213], s[58:59], 0, v[216:217]
	s_mov_b32 m0, s81
	v_lshl_add_u64 v[214:215], s[54:55], 0, v[130:131]
	global_load_lds_dwordx4 v[212:213], off
	v_lshl_add_u64 v[212:213], s[58:59], 0, v[132:133]
	s_add_i32 m0, s81, 0x2000
	s_nop 0
	global_load_lds_dwordx4 v[212:213], off
	v_lshl_add_u64 v[212:213], s[54:55], 0, v[128:129]
	s_mov_b32 m0, s76
	s_nop 0
	global_load_lds_dwordx4 v[212:213], off
	s_mov_b32 m0, s74
	s_nop 0
	global_load_lds_dwordx4 v[214:215], off
	s_waitcnt vmcnt(8)
	s_waitcnt lgkmcnt(0)
	s_barrier
	v_mfma_f32_16x16x32_bf16 v[56:59], v[144:147], v[178:181], v[56:59]
	v_mfma_f32_16x16x32_bf16 v[56:59], v[148:151], v[182:185], v[56:59]
	v_mfma_f32_16x16x32_bf16 v[40:43], v[144:147], v[186:189], v[40:43]
	v_mfma_f32_16x16x32_bf16 v[40:43], v[148:151], v[190:193], v[40:43]
	v_mfma_f32_16x16x32_bf16 v[24:27], v[144:147], v[194:197], v[24:27]
	v_mfma_f32_16x16x32_bf16 v[24:27], v[148:151], v[198:201], v[24:27]
	v_mfma_f32_16x16x32_bf16 v[8:11], v[144:147], v[202:205], v[8:11]
	v_mfma_f32_16x16x32_bf16 v[8:11], v[148:151], v[206:209], v[8:11]
	v_mfma_f32_16x16x32_bf16 v[48:51], v[152:155], v[178:181], v[48:51]
	v_mfma_f32_16x16x32_bf16 v[48:51], v[156:159], v[182:185], v[48:51]
	v_mfma_f32_16x16x32_bf16 v[32:35], v[152:155], v[186:189], v[32:35]
	v_mfma_f32_16x16x32_bf16 v[32:35], v[156:159], v[190:193], v[32:35]
	v_mfma_f32_16x16x32_bf16 v[16:19], v[152:155], v[194:197], v[16:19]
	v_mfma_f32_16x16x32_bf16 v[16:19], v[156:159], v[198:201], v[16:19]
	v_mfma_f32_16x16x32_bf16 v[0:3], v[152:155], v[202:205], v[0:3]
	v_mfma_f32_16x16x32_bf16 v[0:3], v[156:159], v[206:209], v[0:3]
	v_mfma_f32_16x16x32_bf16 v[60:63], v[160:163], v[178:181], v[60:63]
	v_mfma_f32_16x16x32_bf16 v[60:63], v[164:167], v[182:185], v[60:63]
	v_mfma_f32_16x16x32_bf16 v[44:47], v[160:163], v[186:189], v[44:47]
	v_mfma_f32_16x16x32_bf16 v[44:47], v[164:167], v[190:193], v[44:47]
	v_mfma_f32_16x16x32_bf16 v[28:31], v[160:163], v[194:197], v[28:31]
	v_mfma_f32_16x16x32_bf16 v[28:31], v[164:167], v[198:201], v[28:31]
	v_mfma_f32_16x16x32_bf16 v[12:15], v[160:163], v[202:205], v[12:15]
	v_mfma_f32_16x16x32_bf16 v[12:15], v[164:167], v[206:209], v[12:15]
	v_mfma_f32_16x16x32_bf16 v[52:55], v[168:171], v[178:181], v[52:55]
	v_mfma_f32_16x16x32_bf16 v[52:55], v[174:177], v[182:185], v[52:55]
	v_mfma_f32_16x16x32_bf16 v[36:39], v[168:171], v[186:189], v[36:39]
	v_mfma_f32_16x16x32_bf16 v[36:39], v[174:177], v[190:193], v[36:39]
	v_mfma_f32_16x16x32_bf16 v[20:23], v[168:171], v[194:197], v[20:23]
	v_mfma_f32_16x16x32_bf16 v[20:23], v[174:177], v[198:201], v[20:23]
	v_mfma_f32_16x16x32_bf16 v[4:7], v[168:171], v[202:205], v[4:7]
	v_mfma_f32_16x16x32_bf16 v[4:7], v[174:177], v[206:209], v[4:7]
	s_barrier
	s_add_i32 s58, 0, 0x18000
	s_add_i32 s59, 0, 0x1c000
	v_add_u32_e32 v156, s58, v141
	v_add_u32_e32 v173, s59, v141
	ds_read_b128 v[144:147], v156
	ds_read_b128 v[148:151], v156 offset:1024
	ds_read_b128 v[152:155], v156 offset:2048
	ds_read_b128 v[156:159], v156 offset:3072
	ds_read_b128 v[160:163], v173
	ds_read_b128 v[164:167], v173 offset:1024
	ds_read_b128 v[168:171], v173 offset:2048
	ds_read_b128 v[174:177], v173 offset:3072
	s_add_u32 s54, s54, 0x80000
	s_addc_u32 s55, s55, 0
	s_mov_b32 m0, s85
	v_lshl_add_u64 v[218:219], s[54:55], 0, v[128:129]
	ds_read_b128 v[178:181], v143 offset:32768
	ds_read_b128 v[182:185], v143 offset:33792
	ds_read_b128 v[186:189], v143 offset:34816
	ds_read_b128 v[190:193], v143 offset:35840
	ds_read_b128 v[194:197], v143 offset:36864
	ds_read_b128 v[198:201], v143 offset:37888
	ds_read_b128 v[202:205], v143 offset:38912
	ds_read_b128 v[206:209], v143 offset:39936
	global_load_lds_dwordx4 v[218:219], off
	v_lshl_add_u64 v[218:219], s[54:55], 0, v[130:131]
	s_mov_b32 m0, s86
	s_nop 0
	global_load_lds_dwordx4 v[218:219], off
	s_waitcnt vmcnt(8)
	s_waitcnt lgkmcnt(0)
	s_barrier
	v_mfma_f32_16x16x32_bf16 v[120:123], v[144:147], v[178:181], v[120:123]
	v_mfma_f32_16x16x32_bf16 v[120:123], v[148:151], v[182:185], v[120:123]
	v_mfma_f32_16x16x32_bf16 v[104:107], v[144:147], v[186:189], v[104:107]
	v_mfma_f32_16x16x32_bf16 v[104:107], v[148:151], v[190:193], v[104:107]
	v_mfma_f32_16x16x32_bf16 v[88:91], v[144:147], v[194:197], v[88:91]
	v_mfma_f32_16x16x32_bf16 v[88:91], v[148:151], v[198:201], v[88:91]
	v_mfma_f32_16x16x32_bf16 v[72:75], v[144:147], v[202:205], v[72:75]
	v_mfma_f32_16x16x32_bf16 v[72:75], v[148:151], v[206:209], v[72:75]
	v_mfma_f32_16x16x32_bf16 v[112:115], v[152:155], v[178:181], v[112:115]
	v_mfma_f32_16x16x32_bf16 v[112:115], v[156:159], v[182:185], v[112:115]
	v_mfma_f32_16x16x32_bf16 v[96:99], v[152:155], v[186:189], v[96:99]
	v_mfma_f32_16x16x32_bf16 v[96:99], v[156:159], v[190:193], v[96:99]
	v_mfma_f32_16x16x32_bf16 v[80:83], v[152:155], v[194:197], v[80:83]
	v_mfma_f32_16x16x32_bf16 v[80:83], v[156:159], v[198:201], v[80:83]
	v_mfma_f32_16x16x32_bf16 v[64:67], v[152:155], v[202:205], v[64:67]
	v_mfma_f32_16x16x32_bf16 v[64:67], v[156:159], v[206:209], v[64:67]
	v_mfma_f32_16x16x32_bf16 v[124:127], v[160:163], v[178:181], v[124:127]
	v_mfma_f32_16x16x32_bf16 v[124:127], v[164:167], v[182:185], v[124:127]
	v_mfma_f32_16x16x32_bf16 v[108:111], v[160:163], v[186:189], v[108:111]
	v_mfma_f32_16x16x32_bf16 v[108:111], v[164:167], v[190:193], v[108:111]
	v_mfma_f32_16x16x32_bf16 v[92:95], v[160:163], v[194:197], v[92:95]
	v_mfma_f32_16x16x32_bf16 v[92:95], v[164:167], v[198:201], v[92:95]
	v_mfma_f32_16x16x32_bf16 v[76:79], v[160:163], v[202:205], v[76:79]
	v_mfma_f32_16x16x32_bf16 v[76:79], v[164:167], v[206:209], v[76:79]
	v_mfma_f32_16x16x32_bf16 v[116:119], v[168:171], v[178:181], v[116:119]
	v_mfma_f32_16x16x32_bf16 v[116:119], v[174:177], v[182:185], v[116:119]
	v_mfma_f32_16x16x32_bf16 v[100:103], v[168:171], v[186:189], v[100:103]
	v_mfma_f32_16x16x32_bf16 v[100:103], v[174:177], v[190:193], v[100:103]
	v_mfma_f32_16x16x32_bf16 v[84:87], v[168:171], v[194:197], v[84:87]
	v_mfma_f32_16x16x32_bf16 v[84:87], v[174:177], v[198:201], v[84:87]
	v_mfma_f32_16x16x32_bf16 v[68:71], v[168:171], v[202:205], v[68:71]
	v_mfma_f32_16x16x32_bf16 v[68:71], v[174:177], v[206:209], v[68:71]
	s_barrier
	s_add_i32 s54, s58, s50
	v_lshl_add_u64 v[138:139], v[138:139], 0, s[60:61]
	s_mov_b32 m0, s54
	ds_read_b128 v[178:181], v143 offset:49152
	ds_read_b128 v[182:185], v143 offset:50176
	ds_read_b128 v[186:189], v143 offset:51200
	ds_read_b128 v[190:193], v143 offset:52224
	ds_read_b128 v[194:197], v143 offset:53248
	ds_read_b128 v[198:201], v143 offset:54272
	ds_read_b128 v[202:205], v143 offset:55296
	ds_read_b128 v[206:209], v143 offset:56320
	global_load_lds_dwordx4 v[138:139], off
	s_add_i32 m0, s54, 0x2000
	s_add_u32 s52, s52, 0x80080
	v_lshl_add_u64 v[138:139], v[210:211], 0, s[60:61]
	s_addc_u32 s53, s53, 0
	s_add_i32 s54, s59, s50
	global_load_lds_dwordx4 v[138:139], off
	v_lshl_add_u64 v[138:139], s[52:53], 0, v[216:217]
	s_mov_b32 m0, s54
	s_nop 0
	global_load_lds_dwordx4 v[138:139], off
	v_lshl_add_u64 v[138:139], s[52:53], 0, v[132:133]
	s_add_i32 m0, s54, 0x2000
	s_nop 0
	global_load_lds_dwordx4 v[138:139], off
	v_lshl_add_u64 v[138:139], v[212:213], 0, s[60:61]
	s_mov_b32 m0, s87
	s_nop 0
	global_load_lds_dwordx4 v[138:139], off
	v_lshl_add_u64 v[138:139], v[214:215], 0, s[60:61]
	s_mov_b32 m0, s88
	s_nop 0
	global_load_lds_dwordx4 v[138:139], off
	s_waitcnt vmcnt(8)
	s_waitcnt lgkmcnt(0)
	s_barrier
	v_mfma_f32_16x16x32_bf16 v[56:59], v[144:147], v[178:181], v[56:59]
	v_mfma_f32_16x16x32_bf16 v[56:59], v[148:151], v[182:185], v[56:59]
	v_mfma_f32_16x16x32_bf16 v[40:43], v[144:147], v[186:189], v[40:43]
	v_mfma_f32_16x16x32_bf16 v[40:43], v[148:151], v[190:193], v[40:43]
	v_mfma_f32_16x16x32_bf16 v[24:27], v[144:147], v[194:197], v[24:27]
	v_mfma_f32_16x16x32_bf16 v[24:27], v[148:151], v[198:201], v[24:27]
	v_mfma_f32_16x16x32_bf16 v[8:11], v[144:147], v[202:205], v[8:11]
	v_mfma_f32_16x16x32_bf16 v[8:11], v[148:151], v[206:209], v[8:11]
	v_mfma_f32_16x16x32_bf16 v[48:51], v[152:155], v[178:181], v[48:51]
	v_mfma_f32_16x16x32_bf16 v[48:51], v[156:159], v[182:185], v[48:51]
	v_mfma_f32_16x16x32_bf16 v[32:35], v[152:155], v[186:189], v[32:35]
	v_mfma_f32_16x16x32_bf16 v[32:35], v[156:159], v[190:193], v[32:35]
	v_mfma_f32_16x16x32_bf16 v[16:19], v[152:155], v[194:197], v[16:19]
	v_mfma_f32_16x16x32_bf16 v[16:19], v[156:159], v[198:201], v[16:19]
	v_mfma_f32_16x16x32_bf16 v[0:3], v[152:155], v[202:205], v[0:3]
	v_mfma_f32_16x16x32_bf16 v[0:3], v[156:159], v[206:209], v[0:3]
	v_mfma_f32_16x16x32_bf16 v[60:63], v[160:163], v[178:181], v[60:63]
	v_mfma_f32_16x16x32_bf16 v[60:63], v[164:167], v[182:185], v[60:63]
	v_mfma_f32_16x16x32_bf16 v[44:47], v[160:163], v[186:189], v[44:47]
	v_mfma_f32_16x16x32_bf16 v[44:47], v[164:167], v[190:193], v[44:47]
	v_mfma_f32_16x16x32_bf16 v[28:31], v[160:163], v[194:197], v[28:31]
	v_mfma_f32_16x16x32_bf16 v[28:31], v[164:167], v[198:201], v[28:31]
	v_mfma_f32_16x16x32_bf16 v[12:15], v[160:163], v[202:205], v[12:15]
	v_mfma_f32_16x16x32_bf16 v[12:15], v[164:167], v[206:209], v[12:15]
	v_mfma_f32_16x16x32_bf16 v[52:55], v[168:171], v[178:181], v[52:55]
	v_mfma_f32_16x16x32_bf16 v[52:55], v[174:177], v[182:185], v[52:55]
	v_mfma_f32_16x16x32_bf16 v[36:39], v[168:171], v[186:189], v[36:39]
	v_mfma_f32_16x16x32_bf16 v[36:39], v[174:177], v[190:193], v[36:39]
	v_mfma_f32_16x16x32_bf16 v[20:23], v[168:171], v[194:197], v[20:23]
	v_mfma_f32_16x16x32_bf16 v[20:23], v[174:177], v[198:201], v[20:23]
	v_mfma_f32_16x16x32_bf16 v[4:7], v[168:171], v[202:205], v[4:7]
	v_mfma_f32_16x16x32_bf16 v[4:7], v[174:177], v[206:209], v[4:7]
	s_barrier
	s_add_i32 s95, s95, 2
	s_add_u32 s22, s22, 0x100
	s_addc_u32 s23, s23, 0
	s_add_u32 s93, s93, 0x100
	s_addc_u32 s94, s94, 0
	s_cmp_gt_u32 s95, 29
	s_cbranch_scc0 .LBB0_1931
	s_and_b64 vcc, exec, s[38:39]
	s_cbranch_vccz .LBB0_1934
	s_barrier

.LBB0_2081:
	s_add_u32 s22, s18, 0x100
	s_addc_u32 s23, s19, 0
	s_add_i32 s58, 0, 0x10000
	s_cmpk_eq_i32 s95, 0x54
	s_cselect_b32 s55, s7, s23
	s_cselect_b32 s54, s6, s22
	s_cselect_b32 s53, s17, s94
	s_cselect_b32 s52, s16, s93
	s_add_i32 s59, 0, 0x14000
	v_add_u32_e32 v140, s58, v195
	v_add_u32_e32 v166, s59, v195
	ds_read_b128 v[128:131], v140
	ds_read_b128 v[132:135], v140 offset:1024
	ds_read_b128 v[136:139], v140 offset:2048
	ds_read_b128 v[140:143], v140 offset:3072
	ds_read_b128 v[144:147], v166
	ds_read_b128 v[148:151], v166 offset:1024
	ds_read_b128 v[152:155], v166 offset:2048
	ds_read_b128 v[166:169], v166 offset:3072
	v_lshl_add_u64 v[206:207], s[18:19], 0, v[162:163]
	s_add_i32 m0, s76, 0xc000
	ds_read_b128 v[170:173], v197
	ds_read_b128 v[174:177], v197 offset:1024
	ds_read_b128 v[178:181], v197 offset:2048
	ds_read_b128 v[182:185], v197 offset:3072
	ds_read_b128 v[186:189], v197 offset:4096
	ds_read_b128 v[190:193], v197 offset:5120
	ds_read_b128 v[198:201], v197 offset:6144
	ds_read_b128 v[202:205], v197 offset:7168
	global_load_lds_dwordx4 v[206:207], off
	v_lshl_add_u64 v[206:207], s[18:19], 0, v[164:165]
	s_add_i32 m0, s76, 0xe000
	s_nop 0
	global_load_lds_dwordx4 v[206:207], off
	s_waitcnt vmcnt(8)
	s_waitcnt lgkmcnt(0)
	s_barrier
	v_mfma_f32_16x16x32_bf16 v[124:127], v[128:131], v[170:173], v[124:127]
	v_mfma_f32_16x16x32_bf16 v[124:127], v[132:135], v[174:177], v[124:127]
	v_mfma_f32_16x16x32_bf16 v[108:111], v[128:131], v[178:181], v[108:111]
	v_mfma_f32_16x16x32_bf16 v[108:111], v[132:135], v[182:185], v[108:111]
	v_mfma_f32_16x16x32_bf16 v[92:95], v[128:131], v[186:189], v[92:95]
	v_mfma_f32_16x16x32_bf16 v[92:95], v[132:135], v[190:193], v[92:95]
	v_mfma_f32_16x16x32_bf16 v[76:79], v[128:131], v[198:201], v[76:79]
	v_mfma_f32_16x16x32_bf16 v[76:79], v[132:135], v[202:205], v[76:79]
	v_mfma_f32_16x16x32_bf16 v[120:123], v[136:139], v[170:173], v[120:123]
	v_mfma_f32_16x16x32_bf16 v[120:123], v[140:143], v[174:177], v[120:123]
	v_mfma_f32_16x16x32_bf16 v[104:107], v[136:139], v[178:181], v[104:107]
	v_mfma_f32_16x16x32_bf16 v[104:107], v[140:143], v[182:185], v[104:107]
	v_mfma_f32_16x16x32_bf16 v[88:91], v[136:139], v[186:189], v[88:91]
	v_mfma_f32_16x16x32_bf16 v[88:91], v[140:143], v[190:193], v[88:91]
	v_mfma_f32_16x16x32_bf16 v[72:75], v[136:139], v[198:201], v[72:75]
	v_mfma_f32_16x16x32_bf16 v[72:75], v[140:143], v[202:205], v[72:75]
	v_mfma_f32_16x16x32_bf16 v[116:119], v[144:147], v[170:173], v[116:119]
	v_mfma_f32_16x16x32_bf16 v[116:119], v[148:151], v[174:177], v[116:119]
	v_mfma_f32_16x16x32_bf16 v[100:103], v[144:147], v[178:181], v[100:103]
	v_mfma_f32_16x16x32_bf16 v[100:103], v[148:151], v[182:185], v[100:103]
	v_mfma_f32_16x16x32_bf16 v[84:87], v[144:147], v[186:189], v[84:87]
	v_mfma_f32_16x16x32_bf16 v[84:87], v[148:151], v[190:193], v[84:87]
	v_mfma_f32_16x16x32_bf16 v[68:71], v[144:147], v[198:201], v[68:71]
	v_mfma_f32_16x16x32_bf16 v[68:71], v[148:151], v[202:205], v[68:71]
	v_mfma_f32_16x16x32_bf16 v[112:115], v[152:155], v[170:173], v[112:115]
	v_mfma_f32_16x16x32_bf16 v[112:115], v[166:169], v[174:177], v[112:115]
	v_mfma_f32_16x16x32_bf16 v[96:99], v[152:155], v[178:181], v[96:99]
	v_mfma_f32_16x16x32_bf16 v[96:99], v[166:169], v[182:185], v[96:99]
	v_mfma_f32_16x16x32_bf16 v[80:83], v[152:155], v[186:189], v[80:83]
	v_mfma_f32_16x16x32_bf16 v[80:83], v[166:169], v[190:193], v[80:83]
	v_mfma_f32_16x16x32_bf16 v[64:67], v[152:155], v[198:201], v[64:67]
	v_mfma_f32_16x16x32_bf16 v[64:67], v[166:169], v[202:205], v[64:67]
	s_barrier
	s_add_i32 s18, s58, s50
	v_lshl_add_u64 v[206:207], s[52:53], 0, v[216:217]
	s_mov_b32 m0, s18
	ds_read_b128 v[170:173], v197 offset:16384
	ds_read_b128 v[174:177], v197 offset:17408
	ds_read_b128 v[178:181], v197 offset:18432
	ds_read_b128 v[182:185], v197 offset:19456
	ds_read_b128 v[186:189], v197 offset:20480
	ds_read_b128 v[190:193], v197 offset:21504
	ds_read_b128 v[198:201], v197 offset:22528
	ds_read_b128 v[202:205], v197 offset:23552
	global_load_lds_dwordx4 v[206:207], off
	s_add_i32 m0, s18, 0x2000
	s_add_u32 s18, s52, 0x164000
	v_lshl_add_u64 v[208:209], s[52:53], 0, v[160:161]
	s_addc_u32 s19, s53, 0
	s_add_i32 s58, s59, s50
	global_load_lds_dwordx4 v[208:209], off
	v_lshl_add_u64 v[210:211], s[18:19], 0, v[216:217]
	s_mov_b32 m0, s58
	v_lshl_add_u64 v[212:213], s[54:55], 0, v[158:159]
	global_load_lds_dwordx4 v[210:211], off
	v_lshl_add_u64 v[210:211], s[18:19], 0, v[160:161]
	s_add_i32 m0, s58, 0x2000
	s_nop 0
	global_load_lds_dwordx4 v[210:211], off
	v_lshl_add_u64 v[210:211], s[54:55], 0, v[156:157]
	s_mov_b32 m0, s76
	s_nop 0
	global_load_lds_dwordx4 v[210:211], off
	s_mov_b32 m0, s45
	s_nop 0
	global_load_lds_dwordx4 v[212:213], off
	s_waitcnt vmcnt(8)
	s_waitcnt lgkmcnt(0)
	s_barrier
	v_mfma_f32_16x16x32_bf16 v[60:63], v[128:131], v[170:173], v[60:63]
	v_mfma_f32_16x16x32_bf16 v[60:63], v[132:135], v[174:177], v[60:63]
	v_mfma_f32_16x16x32_bf16 v[44:47], v[128:131], v[178:181], v[44:47]
	v_mfma_f32_16x16x32_bf16 v[44:47], v[132:135], v[182:185], v[44:47]
	v_mfma_f32_16x16x32_bf16 v[28:31], v[128:131], v[186:189], v[28:31]
	v_mfma_f32_16x16x32_bf16 v[28:31], v[132:135], v[190:193], v[28:31]
	v_mfma_f32_16x16x32_bf16 v[12:15], v[128:131], v[198:201], v[12:15]
	v_mfma_f32_16x16x32_bf16 v[12:15], v[132:135], v[202:205], v[12:15]
	v_mfma_f32_16x16x32_bf16 v[56:59], v[136:139], v[170:173], v[56:59]
	v_mfma_f32_16x16x32_bf16 v[56:59], v[140:143], v[174:177], v[56:59]
	v_mfma_f32_16x16x32_bf16 v[40:43], v[136:139], v[178:181], v[40:43]
	v_mfma_f32_16x16x32_bf16 v[40:43], v[140:143], v[182:185], v[40:43]
	v_mfma_f32_16x16x32_bf16 v[24:27], v[136:139], v[186:189], v[24:27]
	v_mfma_f32_16x16x32_bf16 v[24:27], v[140:143], v[190:193], v[24:27]
	v_mfma_f32_16x16x32_bf16 v[8:11], v[136:139], v[198:201], v[8:11]
	v_mfma_f32_16x16x32_bf16 v[8:11], v[140:143], v[202:205], v[8:11]
	v_mfma_f32_16x16x32_bf16 v[52:55], v[144:147], v[170:173], v[52:55]
	v_mfma_f32_16x16x32_bf16 v[52:55], v[148:151], v[174:177], v[52:55]
	v_mfma_f32_16x16x32_bf16 v[36:39], v[144:147], v[178:181], v[36:39]
	v_mfma_f32_16x16x32_bf16 v[36:39], v[148:151], v[182:185], v[36:39]
	v_mfma_f32_16x16x32_bf16 v[20:23], v[144:147], v[186:189], v[20:23]
	v_mfma_f32_16x16x32_bf16 v[20:23], v[148:151], v[190:193], v[20:23]
	v_mfma_f32_16x16x32_bf16 v[4:7], v[144:147], v[198:201], v[4:7]
	v_mfma_f32_16x16x32_bf16 v[4:7], v[148:151], v[202:205], v[4:7]
	v_mfma_f32_16x16x32_bf16 v[48:51], v[152:155], v[170:173], v[48:51]
	v_mfma_f32_16x16x32_bf16 v[48:51], v[166:169], v[174:177], v[48:51]
	v_mfma_f32_16x16x32_bf16 v[32:35], v[152:155], v[178:181], v[32:35]
	v_mfma_f32_16x16x32_bf16 v[32:35], v[166:169], v[182:185], v[32:35]
	v_mfma_f32_16x16x32_bf16 v[16:19], v[152:155], v[186:189], v[16:19]
	v_mfma_f32_16x16x32_bf16 v[16:19], v[166:169], v[190:193], v[16:19]
	v_mfma_f32_16x16x32_bf16 v[0:3], v[152:155], v[198:201], v[0:3]
	v_mfma_f32_16x16x32_bf16 v[0:3], v[166:169], v[202:205], v[0:3]
	s_barrier
	s_add_i32 s58, 0, 0x18000
	s_add_i32 s59, 0, 0x1c000
	v_add_u32_e32 v140, s58, v195
	v_add_u32_e32 v166, s59, v195
	ds_read_b128 v[128:131], v140
	ds_read_b128 v[132:135], v140 offset:1024
	ds_read_b128 v[136:139], v140 offset:2048
	ds_read_b128 v[140:143], v140 offset:3072
	ds_read_b128 v[144:147], v166
	ds_read_b128 v[148:151], v166 offset:1024
	ds_read_b128 v[152:155], v166 offset:2048
	ds_read_b128 v[166:169], v166 offset:3072
	s_add_u32 s18, s54, 0x164000
	s_addc_u32 s19, s55, 0
	s_mov_b32 m0, s64
	v_lshl_add_u64 v[214:215], s[18:19], 0, v[156:157]
	ds_read_b128 v[170:173], v197 offset:32768
	ds_read_b128 v[174:177], v197 offset:33792
	ds_read_b128 v[178:181], v197 offset:34816
	ds_read_b128 v[182:185], v197 offset:35840
	ds_read_b128 v[186:189], v197 offset:36864
	ds_read_b128 v[190:193], v197 offset:37888
	ds_read_b128 v[198:201], v197 offset:38912
	ds_read_b128 v[202:205], v197 offset:39936
	global_load_lds_dwordx4 v[214:215], off
	v_lshl_add_u64 v[214:215], s[18:19], 0, v[158:159]
	s_mov_b32 m0, s65
	s_nop 0
	global_load_lds_dwordx4 v[214:215], off
	s_waitcnt vmcnt(8)
	s_waitcnt lgkmcnt(0)
	s_barrier
	v_mfma_f32_16x16x32_bf16 v[124:127], v[128:131], v[170:173], v[124:127]
	v_mfma_f32_16x16x32_bf16 v[124:127], v[132:135], v[174:177], v[124:127]
	v_mfma_f32_16x16x32_bf16 v[108:111], v[128:131], v[178:181], v[108:111]
	v_mfma_f32_16x16x32_bf16 v[108:111], v[132:135], v[182:185], v[108:111]
	v_mfma_f32_16x16x32_bf16 v[92:95], v[128:131], v[186:189], v[92:95]
	v_mfma_f32_16x16x32_bf16 v[92:95], v[132:135], v[190:193], v[92:95]
	v_mfma_f32_16x16x32_bf16 v[76:79], v[128:131], v[198:201], v[76:79]
	v_mfma_f32_16x16x32_bf16 v[76:79], v[132:135], v[202:205], v[76:79]
	v_mfma_f32_16x16x32_bf16 v[120:123], v[136:139], v[170:173], v[120:123]
	v_mfma_f32_16x16x32_bf16 v[120:123], v[140:143], v[174:177], v[120:123]
	v_mfma_f32_16x16x32_bf16 v[104:107], v[136:139], v[178:181], v[104:107]
	v_mfma_f32_16x16x32_bf16 v[104:107], v[140:143], v[182:185], v[104:107]
	v_mfma_f32_16x16x32_bf16 v[88:91], v[136:139], v[186:189], v[88:91]
	v_mfma_f32_16x16x32_bf16 v[88:91], v[140:143], v[190:193], v[88:91]
	v_mfma_f32_16x16x32_bf16 v[72:75], v[136:139], v[198:201], v[72:75]
	v_mfma_f32_16x16x32_bf16 v[72:75], v[140:143], v[202:205], v[72:75]
	v_mfma_f32_16x16x32_bf16 v[116:119], v[144:147], v[170:173], v[116:119]
	v_mfma_f32_16x16x32_bf16 v[116:119], v[148:151], v[174:177], v[116:119]
	v_mfma_f32_16x16x32_bf16 v[100:103], v[144:147], v[178:181], v[100:103]
	v_mfma_f32_16x16x32_bf16 v[100:103], v[148:151], v[182:185], v[100:103]
	v_mfma_f32_16x16x32_bf16 v[84:87], v[144:147], v[186:189], v[84:87]
	v_mfma_f32_16x16x32_bf16 v[84:87], v[148:151], v[190:193], v[84:87]
	v_mfma_f32_16x16x32_bf16 v[68:71], v[144:147], v[198:201], v[68:71]
	v_mfma_f32_16x16x32_bf16 v[68:71], v[148:151], v[202:205], v[68:71]
	v_mfma_f32_16x16x32_bf16 v[112:115], v[152:155], v[170:173], v[112:115]
	v_mfma_f32_16x16x32_bf16 v[112:115], v[166:169], v[174:177], v[112:115]
	v_mfma_f32_16x16x32_bf16 v[96:99], v[152:155], v[178:181], v[96:99]
	v_mfma_f32_16x16x32_bf16 v[96:99], v[166:169], v[182:185], v[96:99]
	v_mfma_f32_16x16x32_bf16 v[80:83], v[152:155], v[186:189], v[80:83]
	v_mfma_f32_16x16x32_bf16 v[80:83], v[166:169], v[190:193], v[80:83]
	v_mfma_f32_16x16x32_bf16 v[64:67], v[152:155], v[198:201], v[64:67]
	v_mfma_f32_16x16x32_bf16 v[64:67], v[166:169], v[202:205], v[64:67]
	s_barrier
	s_add_i32 s18, s58, s50
	v_lshl_add_u64 v[206:207], v[206:207], 0, s[60:61]
	s_mov_b32 m0, s18
	ds_read_b128 v[170:173], v197 offset:49152
	ds_read_b128 v[174:177], v197 offset:50176
	ds_read_b128 v[178:181], v197 offset:51200
	ds_read_b128 v[182:185], v197 offset:52224
	ds_read_b128 v[186:189], v197 offset:53248
	ds_read_b128 v[190:193], v197 offset:54272
	ds_read_b128 v[198:201], v197 offset:55296
	ds_read_b128 v[202:205], v197 offset:56320
	global_load_lds_dwordx4 v[206:207], off
	s_add_i32 m0, s18, 0x2000
	s_add_u32 s18, s52, 0x164080
	v_lshl_add_u64 v[206:207], v[208:209], 0, s[60:61]
	s_addc_u32 s19, s53, 0
	s_add_i32 s52, s59, s50
	global_load_lds_dwordx4 v[206:207], off
	v_lshl_add_u64 v[206:207], s[18:19], 0, v[216:217]
	s_mov_b32 m0, s52
	s_nop 0
	global_load_lds_dwordx4 v[206:207], off
	v_lshl_add_u64 v[206:207], s[18:19], 0, v[160:161]
	s_add_i32 m0, s52, 0x2000
	s_nop 0
	global_load_lds_dwordx4 v[206:207], off
	v_lshl_add_u64 v[206:207], v[210:211], 0, s[60:61]
	s_mov_b32 m0, s85
	s_nop 0
	global_load_lds_dwordx4 v[206:207], off
	v_lshl_add_u64 v[206:207], v[212:213], 0, s[60:61]
	s_mov_b32 m0, s86
	s_nop 0
	global_load_lds_dwordx4 v[206:207], off
	s_waitcnt vmcnt(8)
	s_waitcnt lgkmcnt(0)
	s_barrier
	v_mfma_f32_16x16x32_bf16 v[60:63], v[128:131], v[170:173], v[60:63]
	v_mfma_f32_16x16x32_bf16 v[60:63], v[132:135], v[174:177], v[60:63]
	v_mfma_f32_16x16x32_bf16 v[44:47], v[128:131], v[178:181], v[44:47]
	v_mfma_f32_16x16x32_bf16 v[44:47], v[132:135], v[182:185], v[44:47]
	v_mfma_f32_16x16x32_bf16 v[28:31], v[128:131], v[186:189], v[28:31]
	v_mfma_f32_16x16x32_bf16 v[28:31], v[132:135], v[190:193], v[28:31]
	v_mfma_f32_16x16x32_bf16 v[12:15], v[128:131], v[198:201], v[12:15]
	v_mfma_f32_16x16x32_bf16 v[12:15], v[132:135], v[202:205], v[12:15]
	v_mfma_f32_16x16x32_bf16 v[56:59], v[136:139], v[170:173], v[56:59]
	v_mfma_f32_16x16x32_bf16 v[56:59], v[140:143], v[174:177], v[56:59]
	v_mfma_f32_16x16x32_bf16 v[40:43], v[136:139], v[178:181], v[40:43]
	v_mfma_f32_16x16x32_bf16 v[40:43], v[140:143], v[182:185], v[40:43]
	v_mfma_f32_16x16x32_bf16 v[24:27], v[136:139], v[186:189], v[24:27]
	v_mfma_f32_16x16x32_bf16 v[24:27], v[140:143], v[190:193], v[24:27]
	v_mfma_f32_16x16x32_bf16 v[8:11], v[136:139], v[198:201], v[8:11]
	v_mfma_f32_16x16x32_bf16 v[8:11], v[140:143], v[202:205], v[8:11]
	v_mfma_f32_16x16x32_bf16 v[52:55], v[144:147], v[170:173], v[52:55]
	v_mfma_f32_16x16x32_bf16 v[52:55], v[148:151], v[174:177], v[52:55]
	v_mfma_f32_16x16x32_bf16 v[36:39], v[144:147], v[178:181], v[36:39]
	v_mfma_f32_16x16x32_bf16 v[36:39], v[148:151], v[182:185], v[36:39]
	v_mfma_f32_16x16x32_bf16 v[20:23], v[144:147], v[186:189], v[20:23]
	v_mfma_f32_16x16x32_bf16 v[20:23], v[148:151], v[190:193], v[20:23]
	v_mfma_f32_16x16x32_bf16 v[4:7], v[144:147], v[198:201], v[4:7]
	v_mfma_f32_16x16x32_bf16 v[4:7], v[148:151], v[202:205], v[4:7]
	v_mfma_f32_16x16x32_bf16 v[48:51], v[152:155], v[170:173], v[48:51]
	v_mfma_f32_16x16x32_bf16 v[48:51], v[166:169], v[174:177], v[48:51]
	v_mfma_f32_16x16x32_bf16 v[32:35], v[152:155], v[178:181], v[32:35]
	v_mfma_f32_16x16x32_bf16 v[32:35], v[166:169], v[182:185], v[32:35]
	v_mfma_f32_16x16x32_bf16 v[16:19], v[152:155], v[186:189], v[16:19]
	v_mfma_f32_16x16x32_bf16 v[16:19], v[166:169], v[190:193], v[16:19]
	v_mfma_f32_16x16x32_bf16 v[0:3], v[152:155], v[198:201], v[0:3]
	v_mfma_f32_16x16x32_bf16 v[0:3], v[166:169], v[202:205], v[0:3]
	s_barrier
	s_add_i32 s95, s95, 2
	s_add_u32 s93, s93, 0x100
	s_addc_u32 s94, s94, 0
	s_cmpk_gt_u32 s95, 0x55
	s_mov_b64 s[18:19], s[22:23]
	s_cbranch_scc0 .LBB0_2081
	s_and_b64 vcc, exec, s[38:39]
	s_cbranch_vccz .LBB0_2084
	s_barrier
